# GEMM segments: the two 16-MFMA blocks merged into one 32-MFMA run ordered by B fragment (8 MFMAs per B pair, k-steps adjacent), mid-segment setprio pair removed; on v46 stack
# baseline (speedup 1.0000x reference)
; #define PG8_STAGE(bufoff, gbase, voff) do { _Pragma("unroll") for (int _i = 0; _i < 2; ++_i) \
;         __builtin_amdgcn_global_load_lds((const unsigned*)((const char*)(gbase) + (voff)[_i]), (PG8_LAS unsigned*)(lds + (bufoff) + ldsw + _i * 8192), 16, 0, 0); } while (0)
; #define PG8_LDA(dst, b, h) do { _Pragma("unroll") for (int m = 0; m < 4; ++m) _Pragma("unroll") for (int k = 0; k < 2; ++k) dst[m][k] = *(const PG8_LAS bf16x8*)(lds + PG8_SA(b, h) + aoff + m * 2048 + k * 1024); } while (0)
; #define PG8_LDB(dst, b, h) do { _Pragma("unroll") for (int n = 0; n < 2; ++n) _Pragma("unroll") for (int k = 0; k < 2; ++k) dst[n][k] = *(const PG8_LAS bf16x8*)(lds + PG8_SB(b, h) + boff + n * 2048 + k * 1024); } while (0)
; #define PG8_MMA(ai, bj, At, Bt) do { __builtin_amdgcn_s_setprio(1); _Pragma("unroll") for (int m = 0; m < 4; ++m) _Pragma("unroll") for (int n = 0; n < 2; ++n) _Pragma("unroll") for (int k = 0; k < 2; ++k) \
;         acc[ai][bj][m][n] = __builtin_amdgcn_mfma_f32_16x16x32_bf16(Bt[n][k], At[m][k], acc[ai][bj][m][n], 0, 0, 0); __builtin_amdgcn_s_setprio(0); } while (0)
; #define PG8_WAIT_V(n) asm volatile("s_waitcnt vmcnt(" #n ")" ::: "memory")
; #define PG8_WAIT_L(n) asm volatile("s_waitcnt lgkmcnt(" #n ")" ::: "memory")
; #define PG8_BAR __builtin_amdgcn_s_barrier()
; #define PG8_SCHED __builtin_amdgcn_sched_barrier(0)
; template <class Epi, class Sched, bool ALIGN_EPI = false, bool SP2 = false>
; __device__ __forceinline__ void gemm_phase(PG8_LAS unsigned char* lds, const Gemm g, const Sched& S, const Epi& E) {
;     ...
;             PG8_LDB(B0, 0, 0); PG8_LDB(B1, 0, 1); PG8_SCHED; PG8_LDA(At, 0, 0); PG8_STAGE(PG8_SA(1, 1), a1 + hstep, voffA);
;             PG8_WAIT_V(8); PG8_WAIT_L(0); PG8_BAR; PG8_MMA(0, 0, At, B0); PG8_MMA(0, 1, At, B1); PG8_BAR; PG8_SCHED;
;             PG8_LDA(At, 0, 1); PG8_STAGE(PG8_SB(0, 0), b2, voffB); PG8_STAGE(PG8_SB(0, 1), b2 + hstepB, voffB); PG8_STAGE(PG8_SA(0, 0), a2, voffA);
.LBB0_402:
	ds_read_b128 v[82:85], v178
	ds_read_b128 v[86:89], v178 offset:1024
	ds_read_b128 v[90:93], v178 offset:2048
	ds_read_b128 v[94:97], v178 offset:3072
	ds_read_b128 v[186:189], v179
	ds_read_b128 v[190:193], v179 offset:1024
	ds_read_b128 v[194:197], v179 offset:2048
	ds_read_b128 v[198:201], v179 offset:3072
	s_add_u32 s10, s6, 0xfff00080
	s_addc_u32 s11, s7, -1
	s_cmp_eq_u32 s51, 60
	s_cselect_b32 s35, s23, s11
	s_cselect_b32 s34, s47, s10
	s_cselect_b32 s11, s21, s50
	s_cselect_b32 s10, s48, s49
	v_lshl_add_u64 v[234:235], s[6:7], 0, v[158:159]
	s_add_i32 m0, s29, 0xc000
	ds_read_b128 v[202:205], v180
	ds_read_b128 v[206:209], v180 offset:1024
	ds_read_b128 v[210:213], v180 offset:2048
	ds_read_b128 v[214:217], v180 offset:3072
	ds_read_b128 v[218:221], v180 offset:4096
	ds_read_b128 v[222:225], v180 offset:5120
	ds_read_b128 v[226:229], v180 offset:6144
	ds_read_b128 v[230:233], v180 offset:7168
	global_load_lds_dwordx4 v[234:235], off
	v_lshl_add_u64 v[234:235], s[6:7], 0, v[160:161]
	s_add_i32 m0, s29, 0xe000
	s_nop 0
	global_load_lds_dwordx4 v[234:235], off
	s_waitcnt vmcnt(8)
	s_waitcnt lgkmcnt(0)
	s_barrier
	s_setprio 1
	s_waitcnt lgkmcnt(0)
	v_mfma_f32_16x16x32_bf16 v[142:145], v[82:85], v[202:205], v[142:145]
	v_mfma_f32_16x16x32_bf16 v[142:145], v[86:89], v[206:209], v[142:145]
	v_mfma_f32_16x16x32_bf16 v[138:141], v[90:93], v[202:205], v[138:141]
	v_mfma_f32_16x16x32_bf16 v[138:141], v[94:97], v[206:209], v[138:141]
	v_mfma_f32_16x16x32_bf16 v[134:137], v[186:189], v[202:205], v[134:137]
	v_mfma_f32_16x16x32_bf16 v[134:137], v[190:193], v[206:209], v[134:137]
	v_mfma_f32_16x16x32_bf16 v[130:133], v[194:197], v[202:205], v[130:133]
	v_mfma_f32_16x16x32_bf16 v[130:133], v[198:201], v[206:209], v[130:133]
	v_mfma_f32_16x16x32_bf16 v[126:129], v[82:85], v[210:213], v[126:129]
	v_mfma_f32_16x16x32_bf16 v[126:129], v[86:89], v[214:217], v[126:129]
	v_mfma_f32_16x16x32_bf16 v[122:125], v[90:93], v[210:213], v[122:125]
	v_mfma_f32_16x16x32_bf16 v[122:125], v[94:97], v[214:217], v[122:125]
	v_mfma_f32_16x16x32_bf16 v[118:121], v[186:189], v[210:213], v[118:121]
	v_mfma_f32_16x16x32_bf16 v[118:121], v[190:193], v[214:217], v[118:121]
	v_mfma_f32_16x16x32_bf16 v[114:117], v[194:197], v[210:213], v[114:117]
	v_mfma_f32_16x16x32_bf16 v[114:117], v[198:201], v[214:217], v[114:117]
	v_mfma_f32_16x16x32_bf16 v[110:113], v[82:85], v[218:221], v[110:113]
	v_mfma_f32_16x16x32_bf16 v[110:113], v[86:89], v[222:225], v[110:113]
	v_mfma_f32_16x16x32_bf16 v[106:109], v[90:93], v[218:221], v[106:109]
	v_mfma_f32_16x16x32_bf16 v[106:109], v[94:97], v[222:225], v[106:109]
	v_mfma_f32_16x16x32_bf16 v[102:105], v[186:189], v[218:221], v[102:105]
	v_mfma_f32_16x16x32_bf16 v[102:105], v[190:193], v[222:225], v[102:105]
	v_mfma_f32_16x16x32_bf16 v[98:101], v[194:197], v[218:221], v[98:101]
	v_mfma_f32_16x16x32_bf16 v[98:101], v[198:201], v[222:225], v[98:101]
	v_mfma_f32_16x16x32_bf16 v[78:81], v[82:85], v[226:229], v[78:81]
	v_mfma_f32_16x16x32_bf16 v[78:81], v[86:89], v[230:233], v[78:81]
	v_mfma_f32_16x16x32_bf16 v[74:77], v[90:93], v[226:229], v[74:77]
	v_mfma_f32_16x16x32_bf16 v[74:77], v[94:97], v[230:233], v[74:77]
	v_mfma_f32_16x16x32_bf16 v[70:73], v[186:189], v[226:229], v[70:73]
	v_mfma_f32_16x16x32_bf16 v[70:73], v[190:193], v[230:233], v[70:73]
	v_mfma_f32_16x16x32_bf16 v[66:69], v[194:197], v[226:229], v[66:69]
	v_mfma_f32_16x16x32_bf16 v[66:69], v[198:201], v[230:233], v[66:69]
	s_setprio 0
	s_barrier
	s_add_i32 s52, s42, s37
	v_lshl_add_u64 v[234:235], s[10:11], 0, v[148:149]
	s_mov_b32 m0, s52
	ds_read_b128 v[202:205], v180 offset:16384
	ds_read_b128 v[206:209], v180 offset:17408
	ds_read_b128 v[210:213], v180 offset:18432
	ds_read_b128 v[214:217], v180 offset:19456
	ds_read_b128 v[218:221], v180 offset:20480
	ds_read_b128 v[222:225], v180 offset:21504
	ds_read_b128 v[226:229], v180 offset:22528
	ds_read_b128 v[230:233], v180 offset:23552
	global_load_lds_dwordx4 v[234:235], off
	s_add_i32 m0, s52, 0x2000
	s_add_u32 s52, s10, 0x40000
	v_lshl_add_u64 v[236:237], s[10:11], 0, v[152:153]
	s_addc_u32 s53, s11, 0
	s_add_i32 s54, s43, s37
	global_load_lds_dwordx4 v[236:237], off
	v_lshl_add_u64 v[238:239], s[52:53], 0, v[148:149]
	s_mov_b32 m0, s54
	v_lshl_add_u64 v[240:241], s[34:35], 0, v[150:151]
	global_load_lds_dwordx4 v[238:239], off
	v_lshl_add_u64 v[238:239], s[52:53], 0, v[152:153]
	s_add_i32 m0, s54, 0x2000
	s_nop 0
	global_load_lds_dwordx4 v[238:239], off
	v_lshl_add_u64 v[238:239], s[34:35], 0, v[146:147]
	s_mov_b32 m0, s29
	s_nop 0
	global_load_lds_dwordx4 v[238:239], off
	s_mov_b32 m0, s31
	s_nop 0
	global_load_lds_dwordx4 v[240:241], off
	s_waitcnt vmcnt(8)
	s_waitcnt lgkmcnt(0)
	s_barrier
; #define PG8_STAGE(bufoff, gbase, voff) do { _Pragma("unroll") for (int _i = 0; _i < 2; ++_i) \
;         __builtin_amdgcn_global_load_lds((const unsigned*)((const char*)(gbase) + (voff)[_i]), (PG8_LAS unsigned*)(lds + (bufoff) + ldsw + _i * 8192), 16, 0, 0); } while (0)
; #define PG8_LDA(dst, b, h) do { _Pragma("unroll") for (int m = 0; m < 4; ++m) _Pragma("unroll") for (int k = 0; k < 2; ++k) dst[m][k] = *(const PG8_LAS bf16x8*)(lds + PG8_SA(b, h) + aoff + m * 2048 + k * 1024); } while (0)
; #define PG8_LDB(dst, b, h) do { _Pragma("unroll") for (int n = 0; n < 2; ++n) _Pragma("unroll") for (int k = 0; k < 2; ++k) dst[n][k] = *(const PG8_LAS bf16x8*)(lds + PG8_SB(b, h) + boff + n * 2048 + k * 1024); } while (0)
; #define PG8_MMA(ai, bj, At, Bt) do { __builtin_amdgcn_s_setprio(1); _Pragma("unroll") for (int m = 0; m < 4; ++m) _Pragma("unroll") for (int n = 0; n < 2; ++n) _Pragma("unroll") for (int k = 0; k < 2; ++k) \
;         acc[ai][bj][m][n] = __builtin_amdgcn_mfma_f32_16x16x32_bf16(Bt[n][k], At[m][k], acc[ai][bj][m][n], 0, 0, 0); __builtin_amdgcn_s_setprio(0); } while (0)
; #define PG8_WAIT_V(n) asm volatile("s_waitcnt vmcnt(" #n ")" ::: "memory")
; #define PG8_WAIT_L(n) asm volatile("s_waitcnt lgkmcnt(" #n ")" ::: "memory")
; #define PG8_BAR __builtin_amdgcn_s_barrier()
; #define PG8_SCHED __builtin_amdgcn_sched_barrier(0)
; template <class Epi, class Sched, bool ALIGN_EPI = false, bool SP2 = false>
; __device__ __forceinline__ void gemm_phase(PG8_LAS unsigned char* lds, const Gemm g, const Sched& S, const Epi& E) {
;     ...
;             PG8_WAIT_V(8); PG8_WAIT_L(0); PG8_BAR; PG8_MMA(1, 0, At, B0); PG8_MMA(1, 1, At, B1); PG8_BAR; PG8_SCHED;
;             PG8_LDB(B0, 1, 0); PG8_LDB(B1, 1, 1); PG8_SCHED; PG8_LDA(At, 1, 0); PG8_STAGE(PG8_SA(0, 1), a2 + hstep, voffA);
;             PG8_WAIT_V(8); PG8_WAIT_L(0); PG8_BAR; PG8_MMA(0, 0, At, B0); PG8_MMA(0, 1, At, B1); PG8_BAR; PG8_SCHED;
	s_setprio 1
	s_waitcnt lgkmcnt(0)
	v_mfma_f32_16x16x32_bf16 v[62:65], v[82:85], v[202:205], v[62:65]
	v_mfma_f32_16x16x32_bf16 v[62:65], v[86:89], v[206:209], v[62:65]
	v_mfma_f32_16x16x32_bf16 v[58:61], v[90:93], v[202:205], v[58:61]
	v_mfma_f32_16x16x32_bf16 v[58:61], v[94:97], v[206:209], v[58:61]
	v_mfma_f32_16x16x32_bf16 v[54:57], v[186:189], v[202:205], v[54:57]
	v_mfma_f32_16x16x32_bf16 v[54:57], v[190:193], v[206:209], v[54:57]
	v_mfma_f32_16x16x32_bf16 v[50:53], v[194:197], v[202:205], v[50:53]
	v_mfma_f32_16x16x32_bf16 v[50:53], v[198:201], v[206:209], v[50:53]
	v_mfma_f32_16x16x32_bf16 v[46:49], v[82:85], v[210:213], v[46:49]
	v_mfma_f32_16x16x32_bf16 v[46:49], v[86:89], v[214:217], v[46:49]
	v_mfma_f32_16x16x32_bf16 v[42:45], v[90:93], v[210:213], v[42:45]
	v_mfma_f32_16x16x32_bf16 v[42:45], v[94:97], v[214:217], v[42:45]
	v_mfma_f32_16x16x32_bf16 v[38:41], v[186:189], v[210:213], v[38:41]
	v_mfma_f32_16x16x32_bf16 v[38:41], v[190:193], v[214:217], v[38:41]
	v_mfma_f32_16x16x32_bf16 v[34:37], v[194:197], v[210:213], v[34:37]
	v_mfma_f32_16x16x32_bf16 v[34:37], v[198:201], v[214:217], v[34:37]
	v_mfma_f32_16x16x32_bf16 v[30:33], v[82:85], v[218:221], v[30:33]
	v_mfma_f32_16x16x32_bf16 v[30:33], v[86:89], v[222:225], v[30:33]
	v_mfma_f32_16x16x32_bf16 v[26:29], v[90:93], v[218:221], v[26:29]
	v_mfma_f32_16x16x32_bf16 v[26:29], v[94:97], v[222:225], v[26:29]
	v_mfma_f32_16x16x32_bf16 v[22:25], v[186:189], v[218:221], v[22:25]
	v_mfma_f32_16x16x32_bf16 v[22:25], v[190:193], v[222:225], v[22:25]
	v_mfma_f32_16x16x32_bf16 v[18:21], v[194:197], v[218:221], v[18:21]
	v_mfma_f32_16x16x32_bf16 v[18:21], v[198:201], v[222:225], v[18:21]
	v_mfma_f32_16x16x32_bf16 v[14:17], v[82:85], v[226:229], v[14:17]
	v_mfma_f32_16x16x32_bf16 v[14:17], v[86:89], v[230:233], v[14:17]
	v_mfma_f32_16x16x32_bf16 v[10:13], v[90:93], v[226:229], v[10:13]
	v_mfma_f32_16x16x32_bf16 v[10:13], v[94:97], v[230:233], v[10:13]
	v_mfma_f32_16x16x32_bf16 v[6:9], v[186:189], v[226:229], v[6:9]
	v_mfma_f32_16x16x32_bf16 v[6:9], v[190:193], v[230:233], v[6:9]
	v_mfma_f32_16x16x32_bf16 v[2:5], v[194:197], v[226:229], v[2:5]
	v_mfma_f32_16x16x32_bf16 v[2:5], v[198:201], v[230:233], v[2:5]
	s_setprio 0
	s_barrier
	s_add_i32 s52, 0, 0x18000
	s_add_i32 s53, 0, 0x1c000
	v_add_u32_e32 v94, s52, v1
	v_add_u32_e32 v167, s53, v1
	ds_read_b128 v[82:85], v94
	ds_read_b128 v[86:89], v94 offset:1024
	ds_read_b128 v[90:93], v94 offset:2048
	ds_read_b128 v[94:97], v94 offset:3072
	ds_read_b128 v[186:189], v167
	ds_read_b128 v[190:193], v167 offset:1024
	ds_read_b128 v[194:197], v167 offset:2048
	ds_read_b128 v[198:201], v167 offset:3072
	s_add_u32 s34, s34, 0x100000
	s_addc_u32 s35, s35, 0
	s_mov_b32 m0, s38
	v_lshl_add_u64 v[242:243], s[34:35], 0, v[146:147]
	ds_read_b128 v[202:205], v180 offset:32768
	ds_read_b128 v[206:209], v180 offset:33792
	ds_read_b128 v[210:213], v180 offset:34816
	ds_read_b128 v[214:217], v180 offset:35840
	ds_read_b128 v[218:221], v180 offset:36864
	ds_read_b128 v[222:225], v180 offset:37888
	ds_read_b128 v[226:229], v180 offset:38912
	ds_read_b128 v[230:233], v180 offset:39936
	global_load_lds_dwordx4 v[242:243], off
	v_lshl_add_u64 v[242:243], s[34:35], 0, v[150:151]
	s_mov_b32 m0, s39
	s_nop 0
	global_load_lds_dwordx4 v[242:243], off
	s_waitcnt vmcnt(8)
	s_waitcnt lgkmcnt(0)
	s_barrier
	s_setprio 1
	s_waitcnt lgkmcnt(0)
	v_mfma_f32_16x16x32_bf16 v[142:145], v[82:85], v[202:205], v[142:145]
	v_mfma_f32_16x16x32_bf16 v[142:145], v[86:89], v[206:209], v[142:145]
	v_mfma_f32_16x16x32_bf16 v[138:141], v[90:93], v[202:205], v[138:141]
	v_mfma_f32_16x16x32_bf16 v[138:141], v[94:97], v[206:209], v[138:141]
	v_mfma_f32_16x16x32_bf16 v[134:137], v[186:189], v[202:205], v[134:137]
	v_mfma_f32_16x16x32_bf16 v[134:137], v[190:193], v[206:209], v[134:137]
	v_mfma_f32_16x16x32_bf16 v[130:133], v[194:197], v[202:205], v[130:133]
	v_mfma_f32_16x16x32_bf16 v[130:133], v[198:201], v[206:209], v[130:133]
	v_mfma_f32_16x16x32_bf16 v[126:129], v[82:85], v[210:213], v[126:129]
	v_mfma_f32_16x16x32_bf16 v[126:129], v[86:89], v[214:217], v[126:129]
	v_mfma_f32_16x16x32_bf16 v[122:125], v[90:93], v[210:213], v[122:125]
	v_mfma_f32_16x16x32_bf16 v[122:125], v[94:97], v[214:217], v[122:125]
	v_mfma_f32_16x16x32_bf16 v[118:121], v[186:189], v[210:213], v[118:121]
	v_mfma_f32_16x16x32_bf16 v[118:121], v[190:193], v[214:217], v[118:121]
	v_mfma_f32_16x16x32_bf16 v[114:117], v[194:197], v[210:213], v[114:117]
	v_mfma_f32_16x16x32_bf16 v[114:117], v[198:201], v[214:217], v[114:117]
	v_mfma_f32_16x16x32_bf16 v[110:113], v[82:85], v[218:221], v[110:113]
	v_mfma_f32_16x16x32_bf16 v[110:113], v[86:89], v[222:225], v[110:113]
	v_mfma_f32_16x16x32_bf16 v[106:109], v[90:93], v[218:221], v[106:109]
	v_mfma_f32_16x16x32_bf16 v[106:109], v[94:97], v[222:225], v[106:109]
	v_mfma_f32_16x16x32_bf16 v[102:105], v[186:189], v[218:221], v[102:105]
	v_mfma_f32_16x16x32_bf16 v[102:105], v[190:193], v[222:225], v[102:105]
	v_mfma_f32_16x16x32_bf16 v[98:101], v[194:197], v[218:221], v[98:101]
	v_mfma_f32_16x16x32_bf16 v[98:101], v[198:201], v[222:225], v[98:101]
	v_mfma_f32_16x16x32_bf16 v[78:81], v[82:85], v[226:229], v[78:81]
	v_mfma_f32_16x16x32_bf16 v[78:81], v[86:89], v[230:233], v[78:81]
	v_mfma_f32_16x16x32_bf16 v[74:77], v[90:93], v[226:229], v[74:77]
	v_mfma_f32_16x16x32_bf16 v[74:77], v[94:97], v[230:233], v[74:77]
	v_mfma_f32_16x16x32_bf16 v[70:73], v[186:189], v[226:229], v[70:73]
	v_mfma_f32_16x16x32_bf16 v[70:73], v[190:193], v[230:233], v[70:73]
	v_mfma_f32_16x16x32_bf16 v[66:69], v[194:197], v[226:229], v[66:69]
	v_mfma_f32_16x16x32_bf16 v[66:69], v[198:201], v[230:233], v[66:69]
	s_setprio 0
	s_barrier
; #define PG8_STAGE(bufoff, gbase, voff) do { _Pragma("unroll") for (int _i = 0; _i < 2; ++_i) \
;         __builtin_amdgcn_global_load_lds((const unsigned*)((const char*)(gbase) + (voff)[_i]), (PG8_LAS unsigned*)(lds + (bufoff) + ldsw + _i * 8192), 16, 0, 0); } while (0)
; #define PG8_LDA(dst, b, h) do { _Pragma("unroll") for (int m = 0; m < 4; ++m) _Pragma("unroll") for (int k = 0; k < 2; ++k) dst[m][k] = *(const PG8_LAS bf16x8*)(lds + PG8_SA(b, h) + aoff + m * 2048 + k * 1024); } while (0)
; #define PG8_MMA(ai, bj, At, Bt) do { __builtin_amdgcn_s_setprio(1); _Pragma("unroll") for (int m = 0; m < 4; ++m) _Pragma("unroll") for (int n = 0; n < 2; ++n) _Pragma("unroll") for (int k = 0; k < 2; ++k) \
;         acc[ai][bj][m][n] = __builtin_amdgcn_mfma_f32_16x16x32_bf16(Bt[n][k], At[m][k], acc[ai][bj][m][n], 0, 0, 0); __builtin_amdgcn_s_setprio(0); } while (0)
; #define PG8_WAIT_V(n) asm volatile("s_waitcnt vmcnt(" #n ")" ::: "memory")
; #define PG8_WAIT_L(n) asm volatile("s_waitcnt lgkmcnt(" #n ")" ::: "memory")
; #define PG8_BAR __builtin_amdgcn_s_barrier()
; #define PG8_SCHED __builtin_amdgcn_sched_barrier(0)
; template <class Epi, class Sched, bool ALIGN_EPI = false, bool SP2 = false>
; __device__ __forceinline__ void gemm_phase(PG8_LAS unsigned char* lds, const Gemm g, const Sched& S, const Epi& E) {
;     ...
;             PG8_LDA(At, 1, 1); PG8_STAGE(PG8_SB(1, 0), b3, voffB); PG8_STAGE(PG8_SB(1, 1), b3 + hstepB, voffB); PG8_STAGE(PG8_SA(1, 0), a3, voffA);
;             PG8_WAIT_V(8); PG8_WAIT_L(0); PG8_BAR; PG8_MMA(1, 0, At, B0); PG8_MMA(1, 1, At, B1); PG8_BAR; PG8_SCHED;
	s_add_i32 s34, s52, s37
	v_lshl_add_u64 v[234:235], v[234:235], 0, s[16:17]
	s_mov_b32 m0, s34
	ds_read_b128 v[202:205], v180 offset:49152
	ds_read_b128 v[206:209], v180 offset:50176
	ds_read_b128 v[210:213], v180 offset:51200
	ds_read_b128 v[214:217], v180 offset:52224
	ds_read_b128 v[218:221], v180 offset:53248
	ds_read_b128 v[222:225], v180 offset:54272
	ds_read_b128 v[226:229], v180 offset:55296
	ds_read_b128 v[230:233], v180 offset:56320
	global_load_lds_dwordx4 v[234:235], off
	s_add_i32 m0, s34, 0x2000
	s_add_u32 s10, s10, 0x40080
	v_lshl_add_u64 v[234:235], v[236:237], 0, s[16:17]
	s_addc_u32 s11, s11, 0
	s_add_i32 s34, s53, s37
	global_load_lds_dwordx4 v[234:235], off
	v_lshl_add_u64 v[234:235], s[10:11], 0, v[148:149]
	s_mov_b32 m0, s34
	s_nop 0
	global_load_lds_dwordx4 v[234:235], off
	v_lshl_add_u64 v[234:235], s[10:11], 0, v[152:153]
	s_add_i32 m0, s34, 0x2000
	s_nop 0
	global_load_lds_dwordx4 v[234:235], off
	v_lshl_add_u64 v[234:235], v[238:239], 0, s[16:17]
	s_mov_b32 m0, s40
	s_nop 0
	global_load_lds_dwordx4 v[234:235], off
	v_lshl_add_u64 v[234:235], v[240:241], 0, s[16:17]
	s_mov_b32 m0, s41
	s_nop 0
	global_load_lds_dwordx4 v[234:235], off
	s_waitcnt vmcnt(8)
	s_waitcnt lgkmcnt(0)
	s_barrier
	s_setprio 1
	s_waitcnt lgkmcnt(0)
	v_mfma_f32_16x16x32_bf16 v[62:65], v[82:85], v[202:205], v[62:65]
	v_mfma_f32_16x16x32_bf16 v[62:65], v[86:89], v[206:209], v[62:65]
	v_mfma_f32_16x16x32_bf16 v[58:61], v[90:93], v[202:205], v[58:61]
	v_mfma_f32_16x16x32_bf16 v[58:61], v[94:97], v[206:209], v[58:61]
	v_mfma_f32_16x16x32_bf16 v[54:57], v[186:189], v[202:205], v[54:57]
	v_mfma_f32_16x16x32_bf16 v[54:57], v[190:193], v[206:209], v[54:57]
	v_mfma_f32_16x16x32_bf16 v[50:53], v[194:197], v[202:205], v[50:53]
	v_mfma_f32_16x16x32_bf16 v[50:53], v[198:201], v[206:209], v[50:53]
	v_mfma_f32_16x16x32_bf16 v[46:49], v[82:85], v[210:213], v[46:49]
	v_mfma_f32_16x16x32_bf16 v[46:49], v[86:89], v[214:217], v[46:49]
	v_mfma_f32_16x16x32_bf16 v[42:45], v[90:93], v[210:213], v[42:45]
	v_mfma_f32_16x16x32_bf16 v[42:45], v[94:97], v[214:217], v[42:45]
	v_mfma_f32_16x16x32_bf16 v[38:41], v[186:189], v[210:213], v[38:41]
	v_mfma_f32_16x16x32_bf16 v[38:41], v[190:193], v[214:217], v[38:41]
	v_mfma_f32_16x16x32_bf16 v[34:37], v[194:197], v[210:213], v[34:37]
	v_mfma_f32_16x16x32_bf16 v[34:37], v[198:201], v[214:217], v[34:37]
	v_mfma_f32_16x16x32_bf16 v[30:33], v[82:85], v[218:221], v[30:33]
	v_mfma_f32_16x16x32_bf16 v[30:33], v[86:89], v[222:225], v[30:33]
	v_mfma_f32_16x16x32_bf16 v[26:29], v[90:93], v[218:221], v[26:29]
	v_mfma_f32_16x16x32_bf16 v[26:29], v[94:97], v[222:225], v[26:29]
	v_mfma_f32_16x16x32_bf16 v[22:25], v[186:189], v[218:221], v[22:25]
	v_mfma_f32_16x16x32_bf16 v[22:25], v[190:193], v[222:225], v[22:25]
	v_mfma_f32_16x16x32_bf16 v[18:21], v[194:197], v[218:221], v[18:21]
	v_mfma_f32_16x16x32_bf16 v[18:21], v[198:201], v[222:225], v[18:21]
	v_mfma_f32_16x16x32_bf16 v[14:17], v[82:85], v[226:229], v[14:17]
	v_mfma_f32_16x16x32_bf16 v[14:17], v[86:89], v[230:233], v[14:17]
	v_mfma_f32_16x16x32_bf16 v[10:13], v[90:93], v[226:229], v[10:13]
	v_mfma_f32_16x16x32_bf16 v[10:13], v[94:97], v[230:233], v[10:13]
	v_mfma_f32_16x16x32_bf16 v[6:9], v[186:189], v[226:229], v[6:9]
	v_mfma_f32_16x16x32_bf16 v[6:9], v[190:193], v[230:233], v[6:9]
	v_mfma_f32_16x16x32_bf16 v[2:5], v[194:197], v[226:229], v[2:5]
	v_mfma_f32_16x16x32_bf16 v[2:5], v[198:201], v[230:233], v[2:5]
	s_setprio 0
	s_barrier
	s_add_i32 s51, s51, 2
	s_add_u32 s6, s6, 0x100
	s_addc_u32 s7, s7, 0
	s_add_u32 s49, s49, 0x100
	s_addc_u32 s50, s50, 0
	s_cmp_gt_u32 s51, 61
	s_cbranch_scc0 .LBB0_402
	s_and_b64 vcc, exec, s[18:19]
	s_cbranch_vccz .LBB0_405
	s_barrier

; #define PG8_STAGE(bufoff, gbase, voff) do { _Pragma("unroll") for (int _i = 0; _i < 2; ++_i) \
;         __builtin_amdgcn_global_load_lds((const unsigned*)((const char*)(gbase) + (voff)[_i]), (PG8_LAS unsigned*)(lds + (bufoff) + ldsw + _i * 8192), 16, 0, 0); } while (0)
; #define PG8_LDA(dst, b, h) do { _Pragma("unroll") for (int m = 0; m < 4; ++m) _Pragma("unroll") for (int k = 0; k < 2; ++k) dst[m][k] = *(const PG8_LAS bf16x8*)(lds + PG8_SA(b, h) + aoff + m * 2048 + k * 1024); } while (0)
; #define PG8_LDB(dst, b, h) do { _Pragma("unroll") for (int n = 0; n < 2; ++n) _Pragma("unroll") for (int k = 0; k < 2; ++k) dst[n][k] = *(const PG8_LAS bf16x8*)(lds + PG8_SB(b, h) + boff + n * 2048 + k * 1024); } while (0)
; #define PG8_MMA(ai, bj, At, Bt) do { __builtin_amdgcn_s_setprio(1); _Pragma("unroll") for (int m = 0; m < 4; ++m) _Pragma("unroll") for (int n = 0; n < 2; ++n) _Pragma("unroll") for (int k = 0; k < 2; ++k) \
;         acc[ai][bj][m][n] = __builtin_amdgcn_mfma_f32_16x16x32_bf16(Bt[n][k], At[m][k], acc[ai][bj][m][n], 0, 0, 0); __builtin_amdgcn_s_setprio(0); } while (0)
; #define PG8_WAIT_V(n) asm volatile("s_waitcnt vmcnt(" #n ")" ::: "memory")
; #define PG8_WAIT_L(n) asm volatile("s_waitcnt lgkmcnt(" #n ")" ::: "memory")
; #define PG8_BAR __builtin_amdgcn_s_barrier()
; #define PG8_SCHED __builtin_amdgcn_sched_barrier(0)
; template <class Epi, class Sched, bool ALIGN_EPI = false, bool SP2 = false>
; __device__ __forceinline__ void gemm_phase(PG8_LAS unsigned char* lds, const Gemm g, const Sched& S, const Epi& E) {
;     ...
;             PG8_LDB(B0, 0, 0); PG8_LDB(B1, 0, 1); PG8_SCHED; PG8_LDA(At, 0, 0); PG8_STAGE(PG8_SA(1, 1), a1 + hstep, voffA);
;             PG8_WAIT_V(8); PG8_WAIT_L(0); PG8_BAR; PG8_MMA(0, 0, At, B0); PG8_MMA(0, 1, At, B1); PG8_BAR; PG8_SCHED;
;             PG8_LDA(At, 0, 1); PG8_STAGE(PG8_SB(0, 0), b2, voffB); PG8_STAGE(PG8_SB(0, 1), b2 + hstepB, voffB); PG8_STAGE(PG8_SA(0, 0), a2, voffA);
.LBB0_1759:
	ds_read_b128 v[66:69], v168
	ds_read_b128 v[70:73], v168 offset:1024
	ds_read_b128 v[74:77], v168 offset:2048
	ds_read_b128 v[78:81], v168 offset:3072
	ds_read_b128 v[162:165], v169
	ds_read_b128 v[172:175], v169 offset:1024
	ds_read_b128 v[176:179], v169 offset:2048
	ds_read_b128 v[180:183], v169 offset:3072
	s_add_u32 s34, s30, 0xfff00080
	s_addc_u32 s35, s31, -1
	s_cmp_eq_u32 s63, 60
	s_cselect_b32 s37, s23, s35
	s_cselect_b32 s36, s59, s34
	s_cselect_b32 s35, s21, s62
	s_cselect_b32 s34, s60, s61
	v_lshl_add_u64 v[216:217], s[30:31], 0, v[154:155]
	s_add_i32 m0, s40, 0xc000
	ds_read_b128 v[184:187], v170
	ds_read_b128 v[188:191], v170 offset:1024
	ds_read_b128 v[192:195], v170 offset:2048
	ds_read_b128 v[196:199], v170 offset:3072
	ds_read_b128 v[200:203], v170 offset:4096
	ds_read_b128 v[204:207], v170 offset:5120
	ds_read_b128 v[208:211], v170 offset:6144
	ds_read_b128 v[212:215], v170 offset:7168
	global_load_lds_dwordx4 v[216:217], off
	v_lshl_add_u64 v[216:217], s[30:31], 0, v[156:157]
	s_add_i32 m0, s40, 0xe000
	s_nop 0
	global_load_lds_dwordx4 v[216:217], off
	s_waitcnt vmcnt(8)
	s_waitcnt lgkmcnt(0)
	s_barrier
	s_setprio 1
	s_waitcnt lgkmcnt(0)
	v_mfma_f32_16x16x32_bf16 v[142:145], v[66:69], v[184:187], v[142:145]
	v_mfma_f32_16x16x32_bf16 v[142:145], v[70:73], v[188:191], v[142:145]
	v_mfma_f32_16x16x32_bf16 v[138:141], v[74:77], v[184:187], v[138:141]
	v_mfma_f32_16x16x32_bf16 v[138:141], v[78:81], v[188:191], v[138:141]
	v_mfma_f32_16x16x32_bf16 v[134:137], v[162:165], v[184:187], v[134:137]
	v_mfma_f32_16x16x32_bf16 v[134:137], v[172:175], v[188:191], v[134:137]
	v_mfma_f32_16x16x32_bf16 v[130:133], v[176:179], v[184:187], v[130:133]
	v_mfma_f32_16x16x32_bf16 v[130:133], v[180:183], v[188:191], v[130:133]
	v_mfma_f32_16x16x32_bf16 v[126:129], v[66:69], v[192:195], v[126:129]
	v_mfma_f32_16x16x32_bf16 v[126:129], v[70:73], v[196:199], v[126:129]
	v_mfma_f32_16x16x32_bf16 v[122:125], v[74:77], v[192:195], v[122:125]
	v_mfma_f32_16x16x32_bf16 v[122:125], v[78:81], v[196:199], v[122:125]
	v_mfma_f32_16x16x32_bf16 v[118:121], v[162:165], v[192:195], v[118:121]
	v_mfma_f32_16x16x32_bf16 v[118:121], v[172:175], v[196:199], v[118:121]
	v_mfma_f32_16x16x32_bf16 v[114:117], v[176:179], v[192:195], v[114:117]
	v_mfma_f32_16x16x32_bf16 v[114:117], v[180:183], v[196:199], v[114:117]
	v_mfma_f32_16x16x32_bf16 v[110:113], v[66:69], v[200:203], v[110:113]
	v_mfma_f32_16x16x32_bf16 v[110:113], v[70:73], v[204:207], v[110:113]
	v_mfma_f32_16x16x32_bf16 v[106:109], v[74:77], v[200:203], v[106:109]
	v_mfma_f32_16x16x32_bf16 v[106:109], v[78:81], v[204:207], v[106:109]
	v_mfma_f32_16x16x32_bf16 v[102:105], v[162:165], v[200:203], v[102:105]
	v_mfma_f32_16x16x32_bf16 v[102:105], v[172:175], v[204:207], v[102:105]
	v_mfma_f32_16x16x32_bf16 v[98:101], v[176:179], v[200:203], v[98:101]
	v_mfma_f32_16x16x32_bf16 v[98:101], v[180:183], v[204:207], v[98:101]
	v_mfma_f32_16x16x32_bf16 v[94:97], v[66:69], v[208:211], v[94:97]
	v_mfma_f32_16x16x32_bf16 v[94:97], v[70:73], v[212:215], v[94:97]
	v_mfma_f32_16x16x32_bf16 v[90:93], v[74:77], v[208:211], v[90:93]
	v_mfma_f32_16x16x32_bf16 v[90:93], v[78:81], v[212:215], v[90:93]
	v_mfma_f32_16x16x32_bf16 v[86:89], v[162:165], v[208:211], v[86:89]
	v_mfma_f32_16x16x32_bf16 v[86:89], v[172:175], v[212:215], v[86:89]
	v_mfma_f32_16x16x32_bf16 v[82:85], v[176:179], v[208:211], v[82:85]
	v_mfma_f32_16x16x32_bf16 v[82:85], v[180:183], v[212:215], v[82:85]
	s_setprio 0
	s_barrier
	s_add_i32 s64, s50, s39
	v_lshl_add_u64 v[216:217], s[34:35], 0, v[148:149]
	s_mov_b32 m0, s64
	ds_read_b128 v[184:187], v170 offset:16384
	ds_read_b128 v[188:191], v170 offset:17408
	ds_read_b128 v[192:195], v170 offset:18432
	ds_read_b128 v[196:199], v170 offset:19456
	ds_read_b128 v[200:203], v170 offset:20480
	ds_read_b128 v[204:207], v170 offset:21504
	ds_read_b128 v[208:211], v170 offset:22528
	ds_read_b128 v[212:215], v170 offset:23552
	global_load_lds_dwordx4 v[216:217], off
	s_add_i32 m0, s64, 0x2000
	s_add_u32 s64, s34, 0x100000
	v_lshl_add_u64 v[218:219], s[34:35], 0, v[152:153]
	s_addc_u32 s65, s35, 0
	s_add_i32 s66, s51, s39
	global_load_lds_dwordx4 v[218:219], off
	v_lshl_add_u64 v[220:221], s[64:65], 0, v[148:149]
	s_mov_b32 m0, s66
	v_lshl_add_u64 v[222:223], s[36:37], 0, v[150:151]
	global_load_lds_dwordx4 v[220:221], off
	v_lshl_add_u64 v[220:221], s[64:65], 0, v[152:153]
	s_add_i32 m0, s66, 0x2000
	s_nop 0
	global_load_lds_dwordx4 v[220:221], off
	v_lshl_add_u64 v[220:221], s[36:37], 0, v[146:147]
	s_mov_b32 m0, s40
	s_nop 0
	global_load_lds_dwordx4 v[220:221], off
	s_mov_b32 m0, s41
	s_nop 0
	global_load_lds_dwordx4 v[222:223], off
	s_waitcnt vmcnt(8)
	s_waitcnt lgkmcnt(0)
	s_barrier
; #define PG8_STAGE(bufoff, gbase, voff) do { _Pragma("unroll") for (int _i = 0; _i < 2; ++_i) \
;         __builtin_amdgcn_global_load_lds((const unsigned*)((const char*)(gbase) + (voff)[_i]), (PG8_LAS unsigned*)(lds + (bufoff) + ldsw + _i * 8192), 16, 0, 0); } while (0)
; #define PG8_LDA(dst, b, h) do { _Pragma("unroll") for (int m = 0; m < 4; ++m) _Pragma("unroll") for (int k = 0; k < 2; ++k) dst[m][k] = *(const PG8_LAS bf16x8*)(lds + PG8_SA(b, h) + aoff + m * 2048 + k * 1024); } while (0)
; #define PG8_LDB(dst, b, h) do { _Pragma("unroll") for (int n = 0; n < 2; ++n) _Pragma("unroll") for (int k = 0; k < 2; ++k) dst[n][k] = *(const PG8_LAS bf16x8*)(lds + PG8_SB(b, h) + boff + n * 2048 + k * 1024); } while (0)
; #define PG8_MMA(ai, bj, At, Bt) do { __builtin_amdgcn_s_setprio(1); _Pragma("unroll") for (int m = 0; m < 4; ++m) _Pragma("unroll") for (int n = 0; n < 2; ++n) _Pragma("unroll") for (int k = 0; k < 2; ++k) \
;         acc[ai][bj][m][n] = __builtin_amdgcn_mfma_f32_16x16x32_bf16(Bt[n][k], At[m][k], acc[ai][bj][m][n], 0, 0, 0); __builtin_amdgcn_s_setprio(0); } while (0)
; #define PG8_WAIT_V(n) asm volatile("s_waitcnt vmcnt(" #n ")" ::: "memory")
; #define PG8_WAIT_L(n) asm volatile("s_waitcnt lgkmcnt(" #n ")" ::: "memory")
; #define PG8_BAR __builtin_amdgcn_s_barrier()
; #define PG8_SCHED __builtin_amdgcn_sched_barrier(0)
; template <class Epi, class Sched, bool ALIGN_EPI = false, bool SP2 = false>
; __device__ __forceinline__ void gemm_phase(PG8_LAS unsigned char* lds, const Gemm g, const Sched& S, const Epi& E) {
;     ...
;             PG8_WAIT_V(8); PG8_WAIT_L(0); PG8_BAR; PG8_MMA(1, 0, At, B0); PG8_MMA(1, 1, At, B1); PG8_BAR; PG8_SCHED;
;             PG8_LDB(B0, 1, 0); PG8_LDB(B1, 1, 1); PG8_SCHED; PG8_LDA(At, 1, 0); PG8_STAGE(PG8_SA(0, 1), a2 + hstep, voffA);
;             PG8_WAIT_V(8); PG8_WAIT_L(0); PG8_BAR; PG8_MMA(0, 0, At, B0); PG8_MMA(0, 1, At, B1); PG8_BAR; PG8_SCHED;
	s_setprio 1
	s_waitcnt lgkmcnt(0)
	v_mfma_f32_16x16x32_bf16 v[62:65], v[66:69], v[184:187], v[62:65]
	v_mfma_f32_16x16x32_bf16 v[62:65], v[70:73], v[188:191], v[62:65]
	v_mfma_f32_16x16x32_bf16 v[58:61], v[74:77], v[184:187], v[58:61]
	v_mfma_f32_16x16x32_bf16 v[58:61], v[78:81], v[188:191], v[58:61]
	v_mfma_f32_16x16x32_bf16 v[54:57], v[162:165], v[184:187], v[54:57]
	v_mfma_f32_16x16x32_bf16 v[54:57], v[172:175], v[188:191], v[54:57]
	v_mfma_f32_16x16x32_bf16 v[50:53], v[176:179], v[184:187], v[50:53]
	v_mfma_f32_16x16x32_bf16 v[50:53], v[180:183], v[188:191], v[50:53]
	v_mfma_f32_16x16x32_bf16 v[46:49], v[66:69], v[192:195], v[46:49]
	v_mfma_f32_16x16x32_bf16 v[46:49], v[70:73], v[196:199], v[46:49]
	v_mfma_f32_16x16x32_bf16 v[42:45], v[74:77], v[192:195], v[42:45]
	v_mfma_f32_16x16x32_bf16 v[42:45], v[78:81], v[196:199], v[42:45]
	v_mfma_f32_16x16x32_bf16 v[38:41], v[162:165], v[192:195], v[38:41]
	v_mfma_f32_16x16x32_bf16 v[38:41], v[172:175], v[196:199], v[38:41]
	v_mfma_f32_16x16x32_bf16 v[34:37], v[176:179], v[192:195], v[34:37]
	v_mfma_f32_16x16x32_bf16 v[34:37], v[180:183], v[196:199], v[34:37]
	v_mfma_f32_16x16x32_bf16 v[30:33], v[66:69], v[200:203], v[30:33]
	v_mfma_f32_16x16x32_bf16 v[30:33], v[70:73], v[204:207], v[30:33]
	v_mfma_f32_16x16x32_bf16 v[26:29], v[74:77], v[200:203], v[26:29]
	v_mfma_f32_16x16x32_bf16 v[26:29], v[78:81], v[204:207], v[26:29]
	v_mfma_f32_16x16x32_bf16 v[14:17], v[162:165], v[200:203], v[14:17]
	v_mfma_f32_16x16x32_bf16 v[14:17], v[172:175], v[204:207], v[14:17]
	v_mfma_f32_16x16x32_bf16 v[10:13], v[176:179], v[200:203], v[10:13]
	v_mfma_f32_16x16x32_bf16 v[10:13], v[180:183], v[204:207], v[10:13]
	v_mfma_f32_16x16x32_bf16 v[22:25], v[66:69], v[208:211], v[22:25]
	v_mfma_f32_16x16x32_bf16 v[22:25], v[70:73], v[212:215], v[22:25]
	v_mfma_f32_16x16x32_bf16 v[18:21], v[74:77], v[208:211], v[18:21]
	v_mfma_f32_16x16x32_bf16 v[18:21], v[78:81], v[212:215], v[18:21]
	v_mfma_f32_16x16x32_bf16 v[6:9], v[162:165], v[208:211], v[6:9]
	v_mfma_f32_16x16x32_bf16 v[6:9], v[172:175], v[212:215], v[6:9]
	v_mfma_f32_16x16x32_bf16 v[2:5], v[176:179], v[208:211], v[2:5]
	v_mfma_f32_16x16x32_bf16 v[2:5], v[180:183], v[212:215], v[2:5]
	s_setprio 0
	s_barrier
	s_add_i32 s64, 0, 0x18000
	s_add_i32 s65, 0, 0x1c000
	v_add_u32_e32 v78, s64, v166
	v_add_u32_e32 v171, s65, v166
	ds_read_b128 v[66:69], v78
	ds_read_b128 v[70:73], v78 offset:1024
	ds_read_b128 v[74:77], v78 offset:2048
	ds_read_b128 v[78:81], v78 offset:3072
	ds_read_b128 v[162:165], v171
	ds_read_b128 v[172:175], v171 offset:1024
	ds_read_b128 v[176:179], v171 offset:2048
	ds_read_b128 v[180:183], v171 offset:3072
	s_add_u32 s36, s36, 0x100000
	s_addc_u32 s37, s37, 0
	s_mov_b32 m0, s42
	v_lshl_add_u64 v[224:225], s[36:37], 0, v[146:147]
	ds_read_b128 v[184:187], v170 offset:32768
	ds_read_b128 v[188:191], v170 offset:33792
	ds_read_b128 v[192:195], v170 offset:34816
	ds_read_b128 v[196:199], v170 offset:35840
	ds_read_b128 v[200:203], v170 offset:36864
	ds_read_b128 v[204:207], v170 offset:37888
	ds_read_b128 v[208:211], v170 offset:38912
	ds_read_b128 v[212:215], v170 offset:39936
	global_load_lds_dwordx4 v[224:225], off
	v_lshl_add_u64 v[224:225], s[36:37], 0, v[150:151]
	s_mov_b32 m0, s43
	s_nop 0
	global_load_lds_dwordx4 v[224:225], off
	s_waitcnt vmcnt(8)
	s_waitcnt lgkmcnt(0)
	s_barrier
	s_setprio 1
	s_waitcnt lgkmcnt(0)
	v_mfma_f32_16x16x32_bf16 v[142:145], v[66:69], v[184:187], v[142:145]
	v_mfma_f32_16x16x32_bf16 v[142:145], v[70:73], v[188:191], v[142:145]
	v_mfma_f32_16x16x32_bf16 v[138:141], v[74:77], v[184:187], v[138:141]
	v_mfma_f32_16x16x32_bf16 v[138:141], v[78:81], v[188:191], v[138:141]
	v_mfma_f32_16x16x32_bf16 v[134:137], v[162:165], v[184:187], v[134:137]
	v_mfma_f32_16x16x32_bf16 v[134:137], v[172:175], v[188:191], v[134:137]
	v_mfma_f32_16x16x32_bf16 v[130:133], v[176:179], v[184:187], v[130:133]
	v_mfma_f32_16x16x32_bf16 v[130:133], v[180:183], v[188:191], v[130:133]
	v_mfma_f32_16x16x32_bf16 v[126:129], v[66:69], v[192:195], v[126:129]
	v_mfma_f32_16x16x32_bf16 v[126:129], v[70:73], v[196:199], v[126:129]
	v_mfma_f32_16x16x32_bf16 v[122:125], v[74:77], v[192:195], v[122:125]
	v_mfma_f32_16x16x32_bf16 v[122:125], v[78:81], v[196:199], v[122:125]
	v_mfma_f32_16x16x32_bf16 v[118:121], v[162:165], v[192:195], v[118:121]
	v_mfma_f32_16x16x32_bf16 v[118:121], v[172:175], v[196:199], v[118:121]
	v_mfma_f32_16x16x32_bf16 v[114:117], v[176:179], v[192:195], v[114:117]
	v_mfma_f32_16x16x32_bf16 v[114:117], v[180:183], v[196:199], v[114:117]
	v_mfma_f32_16x16x32_bf16 v[110:113], v[66:69], v[200:203], v[110:113]
	v_mfma_f32_16x16x32_bf16 v[110:113], v[70:73], v[204:207], v[110:113]
	v_mfma_f32_16x16x32_bf16 v[106:109], v[74:77], v[200:203], v[106:109]
	v_mfma_f32_16x16x32_bf16 v[106:109], v[78:81], v[204:207], v[106:109]
	v_mfma_f32_16x16x32_bf16 v[102:105], v[162:165], v[200:203], v[102:105]
	v_mfma_f32_16x16x32_bf16 v[102:105], v[172:175], v[204:207], v[102:105]
	v_mfma_f32_16x16x32_bf16 v[98:101], v[176:179], v[200:203], v[98:101]
	v_mfma_f32_16x16x32_bf16 v[98:101], v[180:183], v[204:207], v[98:101]
	v_mfma_f32_16x16x32_bf16 v[94:97], v[66:69], v[208:211], v[94:97]
	v_mfma_f32_16x16x32_bf16 v[94:97], v[70:73], v[212:215], v[94:97]
	v_mfma_f32_16x16x32_bf16 v[90:93], v[74:77], v[208:211], v[90:93]
	v_mfma_f32_16x16x32_bf16 v[90:93], v[78:81], v[212:215], v[90:93]
	v_mfma_f32_16x16x32_bf16 v[86:89], v[162:165], v[208:211], v[86:89]
	v_mfma_f32_16x16x32_bf16 v[86:89], v[172:175], v[212:215], v[86:89]
	v_mfma_f32_16x16x32_bf16 v[82:85], v[176:179], v[208:211], v[82:85]
	v_mfma_f32_16x16x32_bf16 v[82:85], v[180:183], v[212:215], v[82:85]
	s_setprio 0
	s_barrier
; #define PG8_STAGE(bufoff, gbase, voff) do { _Pragma("unroll") for (int _i = 0; _i < 2; ++_i) \
;         __builtin_amdgcn_global_load_lds((const unsigned*)((const char*)(gbase) + (voff)[_i]), (PG8_LAS unsigned*)(lds + (bufoff) + ldsw + _i * 8192), 16, 0, 0); } while (0)
; #define PG8_LDA(dst, b, h) do { _Pragma("unroll") for (int m = 0; m < 4; ++m) _Pragma("unroll") for (int k = 0; k < 2; ++k) dst[m][k] = *(const PG8_LAS bf16x8*)(lds + PG8_SA(b, h) + aoff + m * 2048 + k * 1024); } while (0)
; #define PG8_MMA(ai, bj, At, Bt) do { __builtin_amdgcn_s_setprio(1); _Pragma("unroll") for (int m = 0; m < 4; ++m) _Pragma("unroll") for (int n = 0; n < 2; ++n) _Pragma("unroll") for (int k = 0; k < 2; ++k) \
;         acc[ai][bj][m][n] = __builtin_amdgcn_mfma_f32_16x16x32_bf16(Bt[n][k], At[m][k], acc[ai][bj][m][n], 0, 0, 0); __builtin_amdgcn_s_setprio(0); } while (0)
; #define PG8_WAIT_V(n) asm volatile("s_waitcnt vmcnt(" #n ")" ::: "memory")
; #define PG8_WAIT_L(n) asm volatile("s_waitcnt lgkmcnt(" #n ")" ::: "memory")
; #define PG8_BAR __builtin_amdgcn_s_barrier()
; #define PG8_SCHED __builtin_amdgcn_sched_barrier(0)
; template <class Epi, class Sched, bool ALIGN_EPI = false, bool SP2 = false>
; __device__ __forceinline__ void gemm_phase(PG8_LAS unsigned char* lds, const Gemm g, const Sched& S, const Epi& E) {
;     ...
;             PG8_LDA(At, 1, 1); PG8_STAGE(PG8_SB(1, 0), b3, voffB); PG8_STAGE(PG8_SB(1, 1), b3 + hstepB, voffB); PG8_STAGE(PG8_SA(1, 0), a3, voffA);
;             PG8_WAIT_V(8); PG8_WAIT_L(0); PG8_BAR; PG8_MMA(1, 0, At, B0); PG8_MMA(1, 1, At, B1); PG8_BAR; PG8_SCHED;
	s_add_i32 s36, s64, s39
	v_lshl_add_u64 v[216:217], v[216:217], 0, s[6:7]
	s_mov_b32 m0, s36
	ds_read_b128 v[184:187], v170 offset:49152
	ds_read_b128 v[188:191], v170 offset:50176
	ds_read_b128 v[192:195], v170 offset:51200
	ds_read_b128 v[196:199], v170 offset:52224
	ds_read_b128 v[200:203], v170 offset:53248
	ds_read_b128 v[204:207], v170 offset:54272
	ds_read_b128 v[208:211], v170 offset:55296
	ds_read_b128 v[212:215], v170 offset:56320
	global_load_lds_dwordx4 v[216:217], off
	s_add_i32 m0, s36, 0x2000
	s_add_u32 s34, s34, 0x100080
	v_lshl_add_u64 v[216:217], v[218:219], 0, s[6:7]
	s_addc_u32 s35, s35, 0
	s_add_i32 s36, s65, s39
	global_load_lds_dwordx4 v[216:217], off
	v_lshl_add_u64 v[216:217], s[34:35], 0, v[148:149]
	s_mov_b32 m0, s36
	s_nop 0
	global_load_lds_dwordx4 v[216:217], off
	v_lshl_add_u64 v[216:217], s[34:35], 0, v[152:153]
	s_add_i32 m0, s36, 0x2000
	s_nop 0
	global_load_lds_dwordx4 v[216:217], off
	v_lshl_add_u64 v[216:217], v[220:221], 0, s[6:7]
	s_mov_b32 m0, s47
	s_nop 0
	global_load_lds_dwordx4 v[216:217], off
	v_lshl_add_u64 v[216:217], v[222:223], 0, s[6:7]
	s_mov_b32 m0, s48
	s_nop 0
	global_load_lds_dwordx4 v[216:217], off
	s_waitcnt vmcnt(8)
	s_waitcnt lgkmcnt(0)
	s_barrier
	s_setprio 1
	s_waitcnt lgkmcnt(0)
	v_mfma_f32_16x16x32_bf16 v[62:65], v[66:69], v[184:187], v[62:65]
	v_mfma_f32_16x16x32_bf16 v[62:65], v[70:73], v[188:191], v[62:65]
	v_mfma_f32_16x16x32_bf16 v[58:61], v[74:77], v[184:187], v[58:61]
	v_mfma_f32_16x16x32_bf16 v[58:61], v[78:81], v[188:191], v[58:61]
	v_mfma_f32_16x16x32_bf16 v[54:57], v[162:165], v[184:187], v[54:57]
	v_mfma_f32_16x16x32_bf16 v[54:57], v[172:175], v[188:191], v[54:57]
	v_mfma_f32_16x16x32_bf16 v[50:53], v[176:179], v[184:187], v[50:53]
	v_mfma_f32_16x16x32_bf16 v[50:53], v[180:183], v[188:191], v[50:53]
	v_mfma_f32_16x16x32_bf16 v[46:49], v[66:69], v[192:195], v[46:49]
	v_mfma_f32_16x16x32_bf16 v[46:49], v[70:73], v[196:199], v[46:49]
	v_mfma_f32_16x16x32_bf16 v[42:45], v[74:77], v[192:195], v[42:45]
	v_mfma_f32_16x16x32_bf16 v[42:45], v[78:81], v[196:199], v[42:45]
	v_mfma_f32_16x16x32_bf16 v[38:41], v[162:165], v[192:195], v[38:41]
	v_mfma_f32_16x16x32_bf16 v[38:41], v[172:175], v[196:199], v[38:41]
	v_mfma_f32_16x16x32_bf16 v[34:37], v[176:179], v[192:195], v[34:37]
	v_mfma_f32_16x16x32_bf16 v[34:37], v[180:183], v[196:199], v[34:37]
	v_mfma_f32_16x16x32_bf16 v[30:33], v[66:69], v[200:203], v[30:33]
	v_mfma_f32_16x16x32_bf16 v[30:33], v[70:73], v[204:207], v[30:33]
	v_mfma_f32_16x16x32_bf16 v[26:29], v[74:77], v[200:203], v[26:29]
	v_mfma_f32_16x16x32_bf16 v[26:29], v[78:81], v[204:207], v[26:29]
	v_mfma_f32_16x16x32_bf16 v[14:17], v[162:165], v[200:203], v[14:17]
	v_mfma_f32_16x16x32_bf16 v[14:17], v[172:175], v[204:207], v[14:17]
	v_mfma_f32_16x16x32_bf16 v[10:13], v[176:179], v[200:203], v[10:13]
	v_mfma_f32_16x16x32_bf16 v[10:13], v[180:183], v[204:207], v[10:13]
	v_mfma_f32_16x16x32_bf16 v[22:25], v[66:69], v[208:211], v[22:25]
	v_mfma_f32_16x16x32_bf16 v[22:25], v[70:73], v[212:215], v[22:25]
	v_mfma_f32_16x16x32_bf16 v[18:21], v[74:77], v[208:211], v[18:21]
	v_mfma_f32_16x16x32_bf16 v[18:21], v[78:81], v[212:215], v[18:21]
	v_mfma_f32_16x16x32_bf16 v[6:9], v[162:165], v[208:211], v[6:9]
	v_mfma_f32_16x16x32_bf16 v[6:9], v[172:175], v[212:215], v[6:9]
	v_mfma_f32_16x16x32_bf16 v[2:5], v[176:179], v[208:211], v[2:5]
	v_mfma_f32_16x16x32_bf16 v[2:5], v[180:183], v[212:215], v[2:5]
	s_setprio 0
	s_barrier
	s_add_i32 s63, s63, 2
	s_add_u32 s30, s30, 0x100
	s_addc_u32 s31, s31, 0
	s_add_u32 s61, s61, 0x100
	s_addc_u32 s62, s62, 0
	s_cmp_gt_u32 s63, 61
	s_cbranch_scc0 .LBB0_1759
	s_and_b64 vcc, exec, s[8:9]
	s_cbranch_vccz .LBB0_1762
	s_barrier

; #define PG8_STAGE(bufoff, gbase, voff) do { _Pragma("unroll") for (int _i = 0; _i < 2; ++_i) \
;         __builtin_amdgcn_global_load_lds((const unsigned*)((const char*)(gbase) + (voff)[_i]), (PG8_LAS unsigned*)(lds + (bufoff) + ldsw + _i * 8192), 16, 0, 0); } while (0)
; #define PG8_LDA(dst, b, h) do { _Pragma("unroll") for (int m = 0; m < 4; ++m) _Pragma("unroll") for (int k = 0; k < 2; ++k) dst[m][k] = *(const PG8_LAS bf16x8*)(lds + PG8_SA(b, h) + aoff + m * 2048 + k * 1024); } while (0)
; #define PG8_LDB(dst, b, h) do { _Pragma("unroll") for (int n = 0; n < 2; ++n) _Pragma("unroll") for (int k = 0; k < 2; ++k) dst[n][k] = *(const PG8_LAS bf16x8*)(lds + PG8_SB(b, h) + boff + n * 2048 + k * 1024); } while (0)
; #define PG8_MMA(ai, bj, At, Bt) do { __builtin_amdgcn_s_setprio(1); _Pragma("unroll") for (int m = 0; m < 4; ++m) _Pragma("unroll") for (int n = 0; n < 2; ++n) _Pragma("unroll") for (int k = 0; k < 2; ++k) \
;         acc[ai][bj][m][n] = __builtin_amdgcn_mfma_f32_16x16x32_bf16(Bt[n][k], At[m][k], acc[ai][bj][m][n], 0, 0, 0); __builtin_amdgcn_s_setprio(0); } while (0)
; #define PG8_WAIT_V(n) asm volatile("s_waitcnt vmcnt(" #n ")" ::: "memory")
; #define PG8_WAIT_L(n) asm volatile("s_waitcnt lgkmcnt(" #n ")" ::: "memory")
; #define PG8_BAR __builtin_amdgcn_s_barrier()
; #define PG8_SCHED __builtin_amdgcn_sched_barrier(0)
; template <class Epi, class Sched, bool ALIGN_EPI = false, bool SP2 = false>
; __device__ __forceinline__ void gemm_phase(PG8_LAS unsigned char* lds, const Gemm g, const Sched& S, const Epi& E) {
;     ...
;             PG8_LDB(B0, 0, 0); PG8_LDB(B1, 0, 1); PG8_SCHED; PG8_LDA(At, 0, 0); PG8_STAGE(PG8_SA(1, 1), a1 + hstep, voffA);
;             PG8_WAIT_V(8); PG8_WAIT_L(0); PG8_BAR; PG8_MMA(0, 0, At, B0); PG8_MMA(0, 1, At, B1); PG8_BAR; PG8_SCHED;
;             PG8_LDA(At, 0, 1); PG8_STAGE(PG8_SB(0, 0), b2, voffB); PG8_STAGE(PG8_SB(0, 1), b2 + hstepB, voffB); PG8_STAGE(PG8_SA(0, 0), a2, voffA);
.LBB0_1889:
	ds_read_b128 v[146:149], v152
	ds_read_b128 v[156:159], v152 offset:1024
	ds_read_b128 v[160:163], v152 offset:2048
	ds_read_b128 v[164:167], v152 offset:3072
	ds_read_b128 v[168:171], v153
	ds_read_b128 v[172:175], v153 offset:1024
	ds_read_b128 v[176:179], v153 offset:2048
	ds_read_b128 v[180:183], v153 offset:3072
	s_add_u32 s16, s14, 0x100
	s_addc_u32 s17, s15, 0
	s_cmp_eq_u32 s44, 60
	s_cselect_b32 s21, s5, s17
	s_cselect_b32 s20, s4, s16
	s_cselect_b32 s19, s13, s43
	s_cselect_b32 s18, s12, s42
	v_lshl_add_u64 v[216:217], s[14:15], 0, v[138:139]
	s_add_i32 m0, s26, 0xc000
	ds_read_b128 v[184:187], v154
	ds_read_b128 v[188:191], v154 offset:1024
	ds_read_b128 v[192:195], v154 offset:2048
	ds_read_b128 v[196:199], v154 offset:3072
	ds_read_b128 v[200:203], v154 offset:4096
	ds_read_b128 v[204:207], v154 offset:5120
	ds_read_b128 v[208:211], v154 offset:6144
	ds_read_b128 v[212:215], v154 offset:7168
	global_load_lds_dwordx4 v[216:217], off
	v_lshl_add_u64 v[216:217], s[14:15], 0, v[140:141]
	s_add_i32 m0, s26, 0xe000
	s_nop 0
	global_load_lds_dwordx4 v[216:217], off
	s_waitcnt vmcnt(8)
	s_waitcnt lgkmcnt(0)
	s_barrier
	s_setprio 1
	s_waitcnt lgkmcnt(0)
	v_mfma_f32_16x16x32_bf16 v[126:129], v[146:149], v[184:187], v[126:129]
	v_mfma_f32_16x16x32_bf16 v[126:129], v[156:159], v[188:191], v[126:129]
	v_mfma_f32_16x16x32_bf16 v[122:125], v[160:163], v[184:187], v[122:125]
	v_mfma_f32_16x16x32_bf16 v[122:125], v[164:167], v[188:191], v[122:125]
	v_mfma_f32_16x16x32_bf16 v[118:121], v[168:171], v[184:187], v[118:121]
	v_mfma_f32_16x16x32_bf16 v[118:121], v[172:175], v[188:191], v[118:121]
	v_mfma_f32_16x16x32_bf16 v[114:117], v[176:179], v[184:187], v[114:117]
	v_mfma_f32_16x16x32_bf16 v[114:117], v[180:183], v[188:191], v[114:117]
	v_mfma_f32_16x16x32_bf16 v[110:113], v[146:149], v[192:195], v[110:113]
	v_mfma_f32_16x16x32_bf16 v[110:113], v[156:159], v[196:199], v[110:113]
	v_mfma_f32_16x16x32_bf16 v[106:109], v[160:163], v[192:195], v[106:109]
	v_mfma_f32_16x16x32_bf16 v[106:109], v[164:167], v[196:199], v[106:109]
	v_mfma_f32_16x16x32_bf16 v[102:105], v[168:171], v[192:195], v[102:105]
	v_mfma_f32_16x16x32_bf16 v[102:105], v[172:175], v[196:199], v[102:105]
	v_mfma_f32_16x16x32_bf16 v[98:101], v[176:179], v[192:195], v[98:101]
	v_mfma_f32_16x16x32_bf16 v[98:101], v[180:183], v[196:199], v[98:101]
	v_mfma_f32_16x16x32_bf16 v[94:97], v[146:149], v[200:203], v[94:97]
	v_mfma_f32_16x16x32_bf16 v[94:97], v[156:159], v[204:207], v[94:97]
	v_mfma_f32_16x16x32_bf16 v[90:93], v[160:163], v[200:203], v[90:93]
	v_mfma_f32_16x16x32_bf16 v[90:93], v[164:167], v[204:207], v[90:93]
	v_mfma_f32_16x16x32_bf16 v[86:89], v[168:171], v[200:203], v[86:89]
	v_mfma_f32_16x16x32_bf16 v[86:89], v[172:175], v[204:207], v[86:89]
	v_mfma_f32_16x16x32_bf16 v[82:85], v[176:179], v[200:203], v[82:85]
	v_mfma_f32_16x16x32_bf16 v[82:85], v[180:183], v[204:207], v[82:85]
	v_mfma_f32_16x16x32_bf16 v[78:81], v[146:149], v[208:211], v[78:81]
	v_mfma_f32_16x16x32_bf16 v[78:81], v[156:159], v[212:215], v[78:81]
	v_mfma_f32_16x16x32_bf16 v[74:77], v[160:163], v[208:211], v[74:77]
	v_mfma_f32_16x16x32_bf16 v[74:77], v[164:167], v[212:215], v[74:77]
	v_mfma_f32_16x16x32_bf16 v[70:73], v[168:171], v[208:211], v[70:73]
	v_mfma_f32_16x16x32_bf16 v[70:73], v[172:175], v[212:215], v[70:73]
	v_mfma_f32_16x16x32_bf16 v[66:69], v[176:179], v[208:211], v[66:69]
	v_mfma_f32_16x16x32_bf16 v[66:69], v[180:183], v[212:215], v[66:69]
	s_setprio 0
	s_barrier
	s_add_i32 s14, s35, s2
	v_lshl_add_u64 v[216:217], s[18:19], 0, v[134:135]
	s_mov_b32 m0, s14
	ds_read_b128 v[184:187], v154 offset:16384
	ds_read_b128 v[188:191], v154 offset:17408
	ds_read_b128 v[192:195], v154 offset:18432
	ds_read_b128 v[196:199], v154 offset:19456
	ds_read_b128 v[200:203], v154 offset:20480
	ds_read_b128 v[204:207], v154 offset:21504
	ds_read_b128 v[208:211], v154 offset:22528
	ds_read_b128 v[212:215], v154 offset:23552
	global_load_lds_dwordx4 v[216:217], off
	s_add_i32 m0, s14, 0x2000
	s_add_u32 s14, s18, 0x108000
	v_lshl_add_u64 v[218:219], s[18:19], 0, v[130:131]
	s_addc_u32 s15, s19, 0
	s_add_i32 s45, s36, s2
	global_load_lds_dwordx4 v[218:219], off
	v_lshl_add_u64 v[220:221], s[14:15], 0, v[134:135]
	s_mov_b32 m0, s45
	v_lshl_add_u64 v[222:223], s[20:21], 0, v[132:133]
	global_load_lds_dwordx4 v[220:221], off
	v_lshl_add_u64 v[220:221], s[14:15], 0, v[130:131]
	s_add_i32 m0, s45, 0x2000
	s_nop 0
	global_load_lds_dwordx4 v[220:221], off
	v_lshl_add_u64 v[220:221], s[20:21], 0, v[136:137]
	s_mov_b32 m0, s26
	s_nop 0
	global_load_lds_dwordx4 v[220:221], off
	s_mov_b32 m0, s27
	s_nop 0
	global_load_lds_dwordx4 v[222:223], off
	s_waitcnt vmcnt(8)
	s_waitcnt lgkmcnt(0)
	s_barrier
; #define PG8_STAGE(bufoff, gbase, voff) do { _Pragma("unroll") for (int _i = 0; _i < 2; ++_i) \
;         __builtin_amdgcn_global_load_lds((const unsigned*)((const char*)(gbase) + (voff)[_i]), (PG8_LAS unsigned*)(lds + (bufoff) + ldsw + _i * 8192), 16, 0, 0); } while (0)
; #define PG8_LDA(dst, b, h) do { _Pragma("unroll") for (int m = 0; m < 4; ++m) _Pragma("unroll") for (int k = 0; k < 2; ++k) dst[m][k] = *(const PG8_LAS bf16x8*)(lds + PG8_SA(b, h) + aoff + m * 2048 + k * 1024); } while (0)
; #define PG8_LDB(dst, b, h) do { _Pragma("unroll") for (int n = 0; n < 2; ++n) _Pragma("unroll") for (int k = 0; k < 2; ++k) dst[n][k] = *(const PG8_LAS bf16x8*)(lds + PG8_SB(b, h) + boff + n * 2048 + k * 1024); } while (0)
; #define PG8_MMA(ai, bj, At, Bt) do { __builtin_amdgcn_s_setprio(1); _Pragma("unroll") for (int m = 0; m < 4; ++m) _Pragma("unroll") for (int n = 0; n < 2; ++n) _Pragma("unroll") for (int k = 0; k < 2; ++k) \
;         acc[ai][bj][m][n] = __builtin_amdgcn_mfma_f32_16x16x32_bf16(Bt[n][k], At[m][k], acc[ai][bj][m][n], 0, 0, 0); __builtin_amdgcn_s_setprio(0); } while (0)
; #define PG8_WAIT_V(n) asm volatile("s_waitcnt vmcnt(" #n ")" ::: "memory")
; #define PG8_WAIT_L(n) asm volatile("s_waitcnt lgkmcnt(" #n ")" ::: "memory")
; #define PG8_BAR __builtin_amdgcn_s_barrier()
; #define PG8_SCHED __builtin_amdgcn_sched_barrier(0)
; template <class Epi, class Sched, bool ALIGN_EPI = false, bool SP2 = false>
; __device__ __forceinline__ void gemm_phase(PG8_LAS unsigned char* lds, const Gemm g, const Sched& S, const Epi& E) {
;     ...
;             PG8_WAIT_V(8); PG8_WAIT_L(0); PG8_BAR; PG8_MMA(1, 0, At, B0); PG8_MMA(1, 1, At, B1); PG8_BAR; PG8_SCHED;
;             PG8_LDB(B0, 1, 0); PG8_LDB(B1, 1, 1); PG8_SCHED; PG8_LDA(At, 1, 0); PG8_STAGE(PG8_SA(0, 1), a2 + hstep, voffA);
;             PG8_WAIT_V(8); PG8_WAIT_L(0); PG8_BAR; PG8_MMA(0, 0, At, B0); PG8_MMA(0, 1, At, B1); PG8_BAR; PG8_SCHED;
	s_setprio 1
	s_waitcnt lgkmcnt(0)
	v_mfma_f32_16x16x32_bf16 v[62:65], v[146:149], v[184:187], v[62:65]
	v_mfma_f32_16x16x32_bf16 v[62:65], v[156:159], v[188:191], v[62:65]
	v_mfma_f32_16x16x32_bf16 v[58:61], v[160:163], v[184:187], v[58:61]
	v_mfma_f32_16x16x32_bf16 v[58:61], v[164:167], v[188:191], v[58:61]
	v_mfma_f32_16x16x32_bf16 v[54:57], v[168:171], v[184:187], v[54:57]
	v_mfma_f32_16x16x32_bf16 v[54:57], v[172:175], v[188:191], v[54:57]
	v_mfma_f32_16x16x32_bf16 v[50:53], v[176:179], v[184:187], v[50:53]
	v_mfma_f32_16x16x32_bf16 v[50:53], v[180:183], v[188:191], v[50:53]
	v_mfma_f32_16x16x32_bf16 v[46:49], v[146:149], v[192:195], v[46:49]
	v_mfma_f32_16x16x32_bf16 v[46:49], v[156:159], v[196:199], v[46:49]
	v_mfma_f32_16x16x32_bf16 v[42:45], v[160:163], v[192:195], v[42:45]
	v_mfma_f32_16x16x32_bf16 v[42:45], v[164:167], v[196:199], v[42:45]
	v_mfma_f32_16x16x32_bf16 v[38:41], v[168:171], v[192:195], v[38:41]
	v_mfma_f32_16x16x32_bf16 v[38:41], v[172:175], v[196:199], v[38:41]
	v_mfma_f32_16x16x32_bf16 v[34:37], v[176:179], v[192:195], v[34:37]
	v_mfma_f32_16x16x32_bf16 v[34:37], v[180:183], v[196:199], v[34:37]
	v_mfma_f32_16x16x32_bf16 v[30:33], v[146:149], v[200:203], v[30:33]
	v_mfma_f32_16x16x32_bf16 v[30:33], v[156:159], v[204:207], v[30:33]
	v_mfma_f32_16x16x32_bf16 v[26:29], v[160:163], v[200:203], v[26:29]
	v_mfma_f32_16x16x32_bf16 v[26:29], v[164:167], v[204:207], v[26:29]
	v_mfma_f32_16x16x32_bf16 v[22:25], v[168:171], v[200:203], v[22:25]
	v_mfma_f32_16x16x32_bf16 v[22:25], v[172:175], v[204:207], v[22:25]
	v_mfma_f32_16x16x32_bf16 v[18:21], v[176:179], v[200:203], v[18:21]
	v_mfma_f32_16x16x32_bf16 v[18:21], v[180:183], v[204:207], v[18:21]
	v_mfma_f32_16x16x32_bf16 v[14:17], v[146:149], v[208:211], v[14:17]
	v_mfma_f32_16x16x32_bf16 v[14:17], v[156:159], v[212:215], v[14:17]
	v_mfma_f32_16x16x32_bf16 v[10:13], v[160:163], v[208:211], v[10:13]
	v_mfma_f32_16x16x32_bf16 v[10:13], v[164:167], v[212:215], v[10:13]
	v_mfma_f32_16x16x32_bf16 v[6:9], v[168:171], v[208:211], v[6:9]
	v_mfma_f32_16x16x32_bf16 v[6:9], v[172:175], v[212:215], v[6:9]
	v_mfma_f32_16x16x32_bf16 v[2:5], v[176:179], v[208:211], v[2:5]
	v_mfma_f32_16x16x32_bf16 v[2:5], v[180:183], v[212:215], v[2:5]
	s_setprio 0
	s_barrier
	s_add_i32 s45, 0, 0x18000
	v_add_u32_e32 v155, s45, v150
	s_add_i32 s46, 0, 0x1c000
	ds_read_b128 v[146:149], v155
	ds_read_b128 v[156:159], v155 offset:1024
	ds_read_b128 v[160:163], v155 offset:2048
	ds_read_b128 v[164:167], v155 offset:3072
	v_add_u32_e32 v155, s46, v150
	ds_read_b128 v[168:171], v155
	ds_read_b128 v[172:175], v155 offset:1024
	ds_read_b128 v[176:179], v155 offset:2048
	ds_read_b128 v[180:183], v155 offset:3072
	s_add_u32 s14, s20, 0x108000
	s_addc_u32 s15, s21, 0
	s_mov_b32 m0, s28
	v_lshl_add_u64 v[224:225], s[14:15], 0, v[136:137]
	ds_read_b128 v[184:187], v154 offset:32768
	ds_read_b128 v[188:191], v154 offset:33792
	ds_read_b128 v[192:195], v154 offset:34816
	ds_read_b128 v[196:199], v154 offset:35840
	ds_read_b128 v[200:203], v154 offset:36864
	ds_read_b128 v[204:207], v154 offset:37888
	ds_read_b128 v[208:211], v154 offset:38912
	ds_read_b128 v[212:215], v154 offset:39936
	global_load_lds_dwordx4 v[224:225], off
	v_lshl_add_u64 v[224:225], s[14:15], 0, v[132:133]
	s_mov_b32 m0, s29
	s_nop 0
	global_load_lds_dwordx4 v[224:225], off
	s_waitcnt vmcnt(8)
	s_waitcnt lgkmcnt(0)
	s_barrier
	s_setprio 1
	s_waitcnt lgkmcnt(0)
	v_mfma_f32_16x16x32_bf16 v[126:129], v[146:149], v[184:187], v[126:129]
	v_mfma_f32_16x16x32_bf16 v[126:129], v[156:159], v[188:191], v[126:129]
	v_mfma_f32_16x16x32_bf16 v[122:125], v[160:163], v[184:187], v[122:125]
	v_mfma_f32_16x16x32_bf16 v[122:125], v[164:167], v[188:191], v[122:125]
	v_mfma_f32_16x16x32_bf16 v[118:121], v[168:171], v[184:187], v[118:121]
	v_mfma_f32_16x16x32_bf16 v[118:121], v[172:175], v[188:191], v[118:121]
	v_mfma_f32_16x16x32_bf16 v[114:117], v[176:179], v[184:187], v[114:117]
	v_mfma_f32_16x16x32_bf16 v[114:117], v[180:183], v[188:191], v[114:117]
	v_mfma_f32_16x16x32_bf16 v[110:113], v[146:149], v[192:195], v[110:113]
	v_mfma_f32_16x16x32_bf16 v[110:113], v[156:159], v[196:199], v[110:113]
	v_mfma_f32_16x16x32_bf16 v[106:109], v[160:163], v[192:195], v[106:109]
	v_mfma_f32_16x16x32_bf16 v[106:109], v[164:167], v[196:199], v[106:109]
	v_mfma_f32_16x16x32_bf16 v[102:105], v[168:171], v[192:195], v[102:105]
	v_mfma_f32_16x16x32_bf16 v[102:105], v[172:175], v[196:199], v[102:105]
	v_mfma_f32_16x16x32_bf16 v[98:101], v[176:179], v[192:195], v[98:101]
	v_mfma_f32_16x16x32_bf16 v[98:101], v[180:183], v[196:199], v[98:101]
	v_mfma_f32_16x16x32_bf16 v[94:97], v[146:149], v[200:203], v[94:97]
	v_mfma_f32_16x16x32_bf16 v[94:97], v[156:159], v[204:207], v[94:97]
	v_mfma_f32_16x16x32_bf16 v[90:93], v[160:163], v[200:203], v[90:93]
	v_mfma_f32_16x16x32_bf16 v[90:93], v[164:167], v[204:207], v[90:93]
	v_mfma_f32_16x16x32_bf16 v[86:89], v[168:171], v[200:203], v[86:89]
	v_mfma_f32_16x16x32_bf16 v[86:89], v[172:175], v[204:207], v[86:89]
	v_mfma_f32_16x16x32_bf16 v[82:85], v[176:179], v[200:203], v[82:85]
	v_mfma_f32_16x16x32_bf16 v[82:85], v[180:183], v[204:207], v[82:85]
	v_mfma_f32_16x16x32_bf16 v[78:81], v[146:149], v[208:211], v[78:81]
	v_mfma_f32_16x16x32_bf16 v[78:81], v[156:159], v[212:215], v[78:81]
	v_mfma_f32_16x16x32_bf16 v[74:77], v[160:163], v[208:211], v[74:77]
	v_mfma_f32_16x16x32_bf16 v[74:77], v[164:167], v[212:215], v[74:77]
	v_mfma_f32_16x16x32_bf16 v[70:73], v[168:171], v[208:211], v[70:73]
	v_mfma_f32_16x16x32_bf16 v[70:73], v[172:175], v[212:215], v[70:73]
	v_mfma_f32_16x16x32_bf16 v[66:69], v[176:179], v[208:211], v[66:69]
	v_mfma_f32_16x16x32_bf16 v[66:69], v[180:183], v[212:215], v[66:69]
	s_setprio 0
	s_barrier
; #define PG8_STAGE(bufoff, gbase, voff) do { _Pragma("unroll") for (int _i = 0; _i < 2; ++_i) \
;         __builtin_amdgcn_global_load_lds((const unsigned*)((const char*)(gbase) + (voff)[_i]), (PG8_LAS unsigned*)(lds + (bufoff) + ldsw + _i * 8192), 16, 0, 0); } while (0)
; #define PG8_LDA(dst, b, h) do { _Pragma("unroll") for (int m = 0; m < 4; ++m) _Pragma("unroll") for (int k = 0; k < 2; ++k) dst[m][k] = *(const PG8_LAS bf16x8*)(lds + PG8_SA(b, h) + aoff + m * 2048 + k * 1024); } while (0)
; #define PG8_MMA(ai, bj, At, Bt) do { __builtin_amdgcn_s_setprio(1); _Pragma("unroll") for (int m = 0; m < 4; ++m) _Pragma("unroll") for (int n = 0; n < 2; ++n) _Pragma("unroll") for (int k = 0; k < 2; ++k) \
;         acc[ai][bj][m][n] = __builtin_amdgcn_mfma_f32_16x16x32_bf16(Bt[n][k], At[m][k], acc[ai][bj][m][n], 0, 0, 0); __builtin_amdgcn_s_setprio(0); } while (0)
; #define PG8_WAIT_V(n) asm volatile("s_waitcnt vmcnt(" #n ")" ::: "memory")
; #define PG8_WAIT_L(n) asm volatile("s_waitcnt lgkmcnt(" #n ")" ::: "memory")
; #define PG8_BAR __builtin_amdgcn_s_barrier()
; #define PG8_SCHED __builtin_amdgcn_sched_barrier(0)
; template <class Epi, class Sched, bool ALIGN_EPI = false, bool SP2 = false>
; __device__ __forceinline__ void gemm_phase(PG8_LAS unsigned char* lds, const Gemm g, const Sched& S, const Epi& E) {
;     ...
;             PG8_LDA(At, 1, 1); PG8_STAGE(PG8_SB(1, 0), b3, voffB); PG8_STAGE(PG8_SB(1, 1), b3 + hstepB, voffB); PG8_STAGE(PG8_SA(1, 0), a3, voffA);
;             PG8_WAIT_V(8); PG8_WAIT_L(0); PG8_BAR; PG8_MMA(1, 0, At, B0); PG8_MMA(1, 1, At, B1); PG8_BAR; PG8_SCHED;
	s_add_i32 s14, s45, s2
	v_lshl_add_u64 v[216:217], v[216:217], 0, s[8:9]
	s_mov_b32 m0, s14
	ds_read_b128 v[184:187], v154 offset:49152
	ds_read_b128 v[188:191], v154 offset:50176
	ds_read_b128 v[192:195], v154 offset:51200
	ds_read_b128 v[196:199], v154 offset:52224
	ds_read_b128 v[200:203], v154 offset:53248
	ds_read_b128 v[204:207], v154 offset:54272
	ds_read_b128 v[208:211], v154 offset:55296
	ds_read_b128 v[212:215], v154 offset:56320
	global_load_lds_dwordx4 v[216:217], off
	s_add_i32 m0, s14, 0x2000
	s_add_u32 s14, s18, 0x108080
	v_lshl_add_u64 v[216:217], v[218:219], 0, s[8:9]
	s_addc_u32 s15, s19, 0
	s_add_i32 s18, s46, s2
	global_load_lds_dwordx4 v[216:217], off
	v_lshl_add_u64 v[216:217], s[14:15], 0, v[134:135]
	s_mov_b32 m0, s18
	s_nop 0
	global_load_lds_dwordx4 v[216:217], off
	v_lshl_add_u64 v[216:217], s[14:15], 0, v[130:131]
	s_add_i32 m0, s18, 0x2000
	s_nop 0
	global_load_lds_dwordx4 v[216:217], off
	v_lshl_add_u64 v[216:217], v[220:221], 0, s[8:9]
	s_mov_b32 m0, s31
	s_nop 0
	global_load_lds_dwordx4 v[216:217], off
	v_lshl_add_u64 v[216:217], v[222:223], 0, s[8:9]
	s_mov_b32 m0, s33
	s_nop 0
	global_load_lds_dwordx4 v[216:217], off
	s_waitcnt vmcnt(8)
	s_waitcnt lgkmcnt(0)
	s_barrier
	s_setprio 1
	s_waitcnt lgkmcnt(0)
	v_mfma_f32_16x16x32_bf16 v[62:65], v[146:149], v[184:187], v[62:65]
	v_mfma_f32_16x16x32_bf16 v[62:65], v[156:159], v[188:191], v[62:65]
	v_mfma_f32_16x16x32_bf16 v[58:61], v[160:163], v[184:187], v[58:61]
	v_mfma_f32_16x16x32_bf16 v[58:61], v[164:167], v[188:191], v[58:61]
	v_mfma_f32_16x16x32_bf16 v[54:57], v[168:171], v[184:187], v[54:57]
	v_mfma_f32_16x16x32_bf16 v[54:57], v[172:175], v[188:191], v[54:57]
	v_mfma_f32_16x16x32_bf16 v[50:53], v[176:179], v[184:187], v[50:53]
	v_mfma_f32_16x16x32_bf16 v[50:53], v[180:183], v[188:191], v[50:53]
	v_mfma_f32_16x16x32_bf16 v[46:49], v[146:149], v[192:195], v[46:49]
	v_mfma_f32_16x16x32_bf16 v[46:49], v[156:159], v[196:199], v[46:49]
	v_mfma_f32_16x16x32_bf16 v[42:45], v[160:163], v[192:195], v[42:45]
	v_mfma_f32_16x16x32_bf16 v[42:45], v[164:167], v[196:199], v[42:45]
	v_mfma_f32_16x16x32_bf16 v[38:41], v[168:171], v[192:195], v[38:41]
	v_mfma_f32_16x16x32_bf16 v[38:41], v[172:175], v[196:199], v[38:41]
	v_mfma_f32_16x16x32_bf16 v[34:37], v[176:179], v[192:195], v[34:37]
	v_mfma_f32_16x16x32_bf16 v[34:37], v[180:183], v[196:199], v[34:37]
	v_mfma_f32_16x16x32_bf16 v[30:33], v[146:149], v[200:203], v[30:33]
	v_mfma_f32_16x16x32_bf16 v[30:33], v[156:159], v[204:207], v[30:33]
	v_mfma_f32_16x16x32_bf16 v[26:29], v[160:163], v[200:203], v[26:29]
	v_mfma_f32_16x16x32_bf16 v[26:29], v[164:167], v[204:207], v[26:29]
	v_mfma_f32_16x16x32_bf16 v[22:25], v[168:171], v[200:203], v[22:25]
	v_mfma_f32_16x16x32_bf16 v[22:25], v[172:175], v[204:207], v[22:25]
	v_mfma_f32_16x16x32_bf16 v[18:21], v[176:179], v[200:203], v[18:21]
	v_mfma_f32_16x16x32_bf16 v[18:21], v[180:183], v[204:207], v[18:21]
	v_mfma_f32_16x16x32_bf16 v[14:17], v[146:149], v[208:211], v[14:17]
	v_mfma_f32_16x16x32_bf16 v[14:17], v[156:159], v[212:215], v[14:17]
	v_mfma_f32_16x16x32_bf16 v[10:13], v[160:163], v[208:211], v[10:13]
	v_mfma_f32_16x16x32_bf16 v[10:13], v[164:167], v[212:215], v[10:13]
	v_mfma_f32_16x16x32_bf16 v[6:9], v[168:171], v[208:211], v[6:9]
	v_mfma_f32_16x16x32_bf16 v[6:9], v[172:175], v[212:215], v[6:9]
	v_mfma_f32_16x16x32_bf16 v[2:5], v[176:179], v[208:211], v[2:5]
	v_mfma_f32_16x16x32_bf16 v[2:5], v[180:183], v[212:215], v[2:5]
	s_setprio 0
	s_barrier
	s_add_i32 s44, s44, 2
	s_add_u32 s42, s42, 0x100
	s_addc_u32 s43, s43, 0
	s_cmp_gt_u32 s44, 61
	s_mov_b64 s[14:15], s[16:17]
	s_cbranch_scc0 .LBB0_1889
	s_and_b64 vcc, exec, s[10:11]
	s_cbranch_vccz .LBB0_1892
	s_barrier

; #define PG8_STAGE(bufoff, gbase, voff) do { _Pragma("unroll") for (int _i = 0; _i < 2; ++_i) \
;         __builtin_amdgcn_global_load_lds((const unsigned*)((const char*)(gbase) + (voff)[_i]), (PG8_LAS unsigned*)(lds + (bufoff) + ldsw + _i * 8192), 16, 0, 0); } while (0)
; #define PG8_LDA(dst, b, h) do { _Pragma("unroll") for (int m = 0; m < 4; ++m) _Pragma("unroll") for (int k = 0; k < 2; ++k) dst[m][k] = *(const PG8_LAS bf16x8*)(lds + PG8_SA(b, h) + aoff + m * 2048 + k * 1024); } while (0)
; #define PG8_LDB(dst, b, h) do { _Pragma("unroll") for (int n = 0; n < 2; ++n) _Pragma("unroll") for (int k = 0; k < 2; ++k) dst[n][k] = *(const PG8_LAS bf16x8*)(lds + PG8_SB(b, h) + boff + n * 2048 + k * 1024); } while (0)
; #define PG8_MMA(ai, bj, At, Bt) do { __builtin_amdgcn_s_setprio(1); _Pragma("unroll") for (int m = 0; m < 4; ++m) _Pragma("unroll") for (int n = 0; n < 2; ++n) _Pragma("unroll") for (int k = 0; k < 2; ++k) \
;         acc[ai][bj][m][n] = __builtin_amdgcn_mfma_f32_16x16x32_bf16(Bt[n][k], At[m][k], acc[ai][bj][m][n], 0, 0, 0); __builtin_amdgcn_s_setprio(0); } while (0)
; #define PG8_WAIT_V(n) asm volatile("s_waitcnt vmcnt(" #n ")" ::: "memory")
; #define PG8_WAIT_L(n) asm volatile("s_waitcnt lgkmcnt(" #n ")" ::: "memory")
; #define PG8_BAR __builtin_amdgcn_s_barrier()
; #define PG8_SCHED __builtin_amdgcn_sched_barrier(0)
; template <class Epi, class Sched, bool ALIGN_EPI = false, bool SP2 = false>
; __device__ __forceinline__ void gemm_phase(PG8_LAS unsigned char* lds, const Gemm g, const Sched& S, const Epi& E) {
;     ...
;             PG8_LDB(B0, 0, 0); PG8_LDB(B1, 0, 1); PG8_SCHED; PG8_LDA(At, 0, 0); PG8_STAGE(PG8_SA(1, 1), a1 + hstep, voffA);
;             PG8_WAIT_V(8); PG8_WAIT_L(0); PG8_BAR; PG8_MMA(0, 0, At, B0); PG8_MMA(0, 1, At, B1); PG8_BAR; PG8_SCHED;
;             PG8_LDA(At, 0, 1); PG8_STAGE(PG8_SB(0, 0), b2, voffB); PG8_STAGE(PG8_SB(0, 1), b2 + hstepB, voffB); PG8_STAGE(PG8_SA(0, 0), a2, voffA);
.LBB0_2165:
	ds_read_b128 v[128:131], v167
	ds_read_b128 v[132:135], v167 offset:1024
	ds_read_b128 v[136:139], v167 offset:2048
	ds_read_b128 v[140:143], v167 offset:3072
	ds_read_b128 v[160:163], v168
	ds_read_b128 v[170:173], v168 offset:1024
	ds_read_b128 v[174:177], v168 offset:2048
	ds_read_b128 v[178:181], v168 offset:3072
	s_add_u32 s16, s14, 0x100
	s_addc_u32 s17, s15, 0
	s_cmpk_eq_i32 s57, 0xa8
	s_cselect_b32 s21, s5, s17
	s_cselect_b32 s20, s4, s16
	s_cselect_b32 s19, s13, s56
	s_cselect_b32 s18, s12, s55
	v_lshl_add_u64 v[214:215], s[14:15], 0, v[152:153]
	s_add_i32 m0, s25, 0xc000
	ds_read_b128 v[182:185], v169
	ds_read_b128 v[186:189], v169 offset:1024
	ds_read_b128 v[190:193], v169 offset:2048
	ds_read_b128 v[194:197], v169 offset:3072
	ds_read_b128 v[198:201], v169 offset:4096
	ds_read_b128 v[202:205], v169 offset:5120
	ds_read_b128 v[206:209], v169 offset:6144
	ds_read_b128 v[210:213], v169 offset:7168
	global_load_lds_dwordx4 v[214:215], off
	v_lshl_add_u64 v[214:215], s[14:15], 0, v[154:155]
	s_add_i32 m0, s25, 0xe000
	s_nop 0
	global_load_lds_dwordx4 v[214:215], off
	s_waitcnt vmcnt(8)
	s_waitcnt lgkmcnt(0)
	s_barrier
	s_setprio 1
	s_waitcnt lgkmcnt(0)
	v_mfma_f32_16x16x32_bf16 v[124:127], v[128:131], v[182:185], v[124:127]
	v_mfma_f32_16x16x32_bf16 v[124:127], v[132:135], v[186:189], v[124:127]
	v_mfma_f32_16x16x32_bf16 v[120:123], v[136:139], v[182:185], v[120:123]
	v_mfma_f32_16x16x32_bf16 v[120:123], v[140:143], v[186:189], v[120:123]
	v_mfma_f32_16x16x32_bf16 v[112:115], v[160:163], v[182:185], v[112:115]
	v_mfma_f32_16x16x32_bf16 v[112:115], v[170:173], v[186:189], v[112:115]
	v_mfma_f32_16x16x32_bf16 v[104:107], v[174:177], v[182:185], v[104:107]
	v_mfma_f32_16x16x32_bf16 v[104:107], v[178:181], v[186:189], v[104:107]
	v_mfma_f32_16x16x32_bf16 v[116:119], v[128:131], v[190:193], v[116:119]
	v_mfma_f32_16x16x32_bf16 v[116:119], v[132:135], v[194:197], v[116:119]
	v_mfma_f32_16x16x32_bf16 v[108:111], v[136:139], v[190:193], v[108:111]
	v_mfma_f32_16x16x32_bf16 v[108:111], v[140:143], v[194:197], v[108:111]
	v_mfma_f32_16x16x32_bf16 v[100:103], v[160:163], v[190:193], v[100:103]
	v_mfma_f32_16x16x32_bf16 v[100:103], v[170:173], v[194:197], v[100:103]
	v_mfma_f32_16x16x32_bf16 v[96:99], v[174:177], v[190:193], v[96:99]
	v_mfma_f32_16x16x32_bf16 v[96:99], v[178:181], v[194:197], v[96:99]
	v_mfma_f32_16x16x32_bf16 v[92:95], v[128:131], v[198:201], v[92:95]
	v_mfma_f32_16x16x32_bf16 v[92:95], v[132:135], v[202:205], v[92:95]
	v_mfma_f32_16x16x32_bf16 v[88:91], v[136:139], v[198:201], v[88:91]
	v_mfma_f32_16x16x32_bf16 v[88:91], v[140:143], v[202:205], v[88:91]
	v_mfma_f32_16x16x32_bf16 v[84:87], v[160:163], v[198:201], v[84:87]
	v_mfma_f32_16x16x32_bf16 v[84:87], v[170:173], v[202:205], v[84:87]
	v_mfma_f32_16x16x32_bf16 v[76:79], v[174:177], v[198:201], v[76:79]
	v_mfma_f32_16x16x32_bf16 v[76:79], v[178:181], v[202:205], v[76:79]
	v_mfma_f32_16x16x32_bf16 v[80:83], v[128:131], v[206:209], v[80:83]
	v_mfma_f32_16x16x32_bf16 v[80:83], v[132:135], v[210:213], v[80:83]
	v_mfma_f32_16x16x32_bf16 v[72:75], v[136:139], v[206:209], v[72:75]
	v_mfma_f32_16x16x32_bf16 v[72:75], v[140:143], v[210:213], v[72:75]
	v_mfma_f32_16x16x32_bf16 v[68:71], v[160:163], v[206:209], v[68:71]
	v_mfma_f32_16x16x32_bf16 v[68:71], v[170:173], v[210:213], v[68:71]
	v_mfma_f32_16x16x32_bf16 v[64:67], v[174:177], v[206:209], v[64:67]
	v_mfma_f32_16x16x32_bf16 v[64:67], v[178:181], v[210:213], v[64:67]
	s_setprio 0
	s_barrier
	s_add_i32 s14, s36, s24
	v_lshl_add_u64 v[214:215], s[18:19], 0, v[146:147]
	s_mov_b32 m0, s14
	ds_read_b128 v[182:185], v169 offset:16384
	ds_read_b128 v[186:189], v169 offset:17408
	ds_read_b128 v[190:193], v169 offset:18432
	ds_read_b128 v[194:197], v169 offset:19456
	ds_read_b128 v[198:201], v169 offset:20480
	ds_read_b128 v[202:205], v169 offset:21504
	ds_read_b128 v[206:209], v169 offset:22528
	ds_read_b128 v[210:213], v169 offset:23552
	global_load_lds_dwordx4 v[214:215], off
	s_add_i32 m0, s14, 0x2000
	s_add_u32 s14, s18, 0x2b0000
	v_lshl_add_u64 v[216:217], s[18:19], 0, v[150:151]
	s_addc_u32 s15, s19, 0
	s_add_i32 s58, s37, s24
	global_load_lds_dwordx4 v[216:217], off
	v_lshl_add_u64 v[218:219], s[14:15], 0, v[146:147]
	s_mov_b32 m0, s58
	v_lshl_add_u64 v[220:221], s[20:21], 0, v[148:149]
	global_load_lds_dwordx4 v[218:219], off
	v_lshl_add_u64 v[218:219], s[14:15], 0, v[150:151]
	s_add_i32 m0, s58, 0x2000
	s_nop 0
	global_load_lds_dwordx4 v[218:219], off
	v_lshl_add_u64 v[218:219], s[20:21], 0, v[144:145]
	s_mov_b32 m0, s25
	s_nop 0
	global_load_lds_dwordx4 v[218:219], off
	s_mov_b32 m0, s26
	s_nop 0
	global_load_lds_dwordx4 v[220:221], off
	s_waitcnt vmcnt(8)
	s_waitcnt lgkmcnt(0)
	s_barrier
; #define PG8_STAGE(bufoff, gbase, voff) do { _Pragma("unroll") for (int _i = 0; _i < 2; ++_i) \
;         __builtin_amdgcn_global_load_lds((const unsigned*)((const char*)(gbase) + (voff)[_i]), (PG8_LAS unsigned*)(lds + (bufoff) + ldsw + _i * 8192), 16, 0, 0); } while (0)
; #define PG8_LDA(dst, b, h) do { _Pragma("unroll") for (int m = 0; m < 4; ++m) _Pragma("unroll") for (int k = 0; k < 2; ++k) dst[m][k] = *(const PG8_LAS bf16x8*)(lds + PG8_SA(b, h) + aoff + m * 2048 + k * 1024); } while (0)
; #define PG8_LDB(dst, b, h) do { _Pragma("unroll") for (int n = 0; n < 2; ++n) _Pragma("unroll") for (int k = 0; k < 2; ++k) dst[n][k] = *(const PG8_LAS bf16x8*)(lds + PG8_SB(b, h) + boff + n * 2048 + k * 1024); } while (0)
; #define PG8_MMA(ai, bj, At, Bt) do { __builtin_amdgcn_s_setprio(1); _Pragma("unroll") for (int m = 0; m < 4; ++m) _Pragma("unroll") for (int n = 0; n < 2; ++n) _Pragma("unroll") for (int k = 0; k < 2; ++k) \
;         acc[ai][bj][m][n] = __builtin_amdgcn_mfma_f32_16x16x32_bf16(Bt[n][k], At[m][k], acc[ai][bj][m][n], 0, 0, 0); __builtin_amdgcn_s_setprio(0); } while (0)
; #define PG8_WAIT_V(n) asm volatile("s_waitcnt vmcnt(" #n ")" ::: "memory")
; #define PG8_WAIT_L(n) asm volatile("s_waitcnt lgkmcnt(" #n ")" ::: "memory")
; #define PG8_BAR __builtin_amdgcn_s_barrier()
; #define PG8_SCHED __builtin_amdgcn_sched_barrier(0)
; template <class Epi, class Sched, bool ALIGN_EPI = false, bool SP2 = false>
; __device__ __forceinline__ void gemm_phase(PG8_LAS unsigned char* lds, const Gemm g, const Sched& S, const Epi& E) {
;     ...
;             PG8_WAIT_V(8); PG8_WAIT_L(0); PG8_BAR; PG8_MMA(1, 0, At, B0); PG8_MMA(1, 1, At, B1); PG8_BAR; PG8_SCHED;
;             PG8_LDB(B0, 1, 0); PG8_LDB(B1, 1, 1); PG8_SCHED; PG8_LDA(At, 1, 0); PG8_STAGE(PG8_SA(0, 1), a2 + hstep, voffA);
;             PG8_WAIT_V(8); PG8_WAIT_L(0); PG8_BAR; PG8_MMA(0, 0, At, B0); PG8_MMA(0, 1, At, B1); PG8_BAR; PG8_SCHED;
;             PG8_LDA(At, 1, 1); PG8_STAGE(PG8_SB(1, 0), b3, voffB); PG8_STAGE(PG8_SB(1, 1), b3 + hstepB, voffB); PG8_STAGE(PG8_SA(1, 0), a3, voffA);
;             PG8_WAIT_V(8); PG8_WAIT_L(0); PG8_BAR; PG8_MMA(1, 0, At, B0); PG8_MMA(1, 1, At, B1); PG8_BAR; PG8_SCHED;
	s_setprio 1
	s_waitcnt lgkmcnt(0)
	v_mfma_f32_16x16x32_bf16 v[60:63], v[128:131], v[182:185], v[60:63]
	v_mfma_f32_16x16x32_bf16 v[60:63], v[132:135], v[186:189], v[60:63]
	v_mfma_f32_16x16x32_bf16 v[56:59], v[136:139], v[182:185], v[56:59]
	v_mfma_f32_16x16x32_bf16 v[56:59], v[140:143], v[186:189], v[56:59]
	v_mfma_f32_16x16x32_bf16 v[52:55], v[160:163], v[182:185], v[52:55]
	v_mfma_f32_16x16x32_bf16 v[52:55], v[170:173], v[186:189], v[52:55]
	v_mfma_f32_16x16x32_bf16 v[44:47], v[174:177], v[182:185], v[44:47]
	v_mfma_f32_16x16x32_bf16 v[44:47], v[178:181], v[186:189], v[44:47]
	v_mfma_f32_16x16x32_bf16 v[48:51], v[128:131], v[190:193], v[48:51]
	v_mfma_f32_16x16x32_bf16 v[48:51], v[132:135], v[194:197], v[48:51]
	v_mfma_f32_16x16x32_bf16 v[40:43], v[136:139], v[190:193], v[40:43]
	v_mfma_f32_16x16x32_bf16 v[40:43], v[140:143], v[194:197], v[40:43]
	v_mfma_f32_16x16x32_bf16 v[36:39], v[160:163], v[190:193], v[36:39]
	v_mfma_f32_16x16x32_bf16 v[36:39], v[170:173], v[194:197], v[36:39]
	v_mfma_f32_16x16x32_bf16 v[32:35], v[174:177], v[190:193], v[32:35]
	v_mfma_f32_16x16x32_bf16 v[32:35], v[178:181], v[194:197], v[32:35]
	v_mfma_f32_16x16x32_bf16 v[28:31], v[128:131], v[198:201], v[28:31]
	v_mfma_f32_16x16x32_bf16 v[28:31], v[132:135], v[202:205], v[28:31]
	v_mfma_f32_16x16x32_bf16 v[24:27], v[136:139], v[198:201], v[24:27]
	v_mfma_f32_16x16x32_bf16 v[24:27], v[140:143], v[202:205], v[24:27]
	v_mfma_f32_16x16x32_bf16 v[16:19], v[160:163], v[198:201], v[16:19]
	v_mfma_f32_16x16x32_bf16 v[16:19], v[170:173], v[202:205], v[16:19]
	v_mfma_f32_16x16x32_bf16 v[8:11], v[174:177], v[198:201], v[8:11]
	v_mfma_f32_16x16x32_bf16 v[8:11], v[178:181], v[202:205], v[8:11]
	v_mfma_f32_16x16x32_bf16 v[20:23], v[128:131], v[206:209], v[20:23]
	v_mfma_f32_16x16x32_bf16 v[20:23], v[132:135], v[210:213], v[20:23]
	v_mfma_f32_16x16x32_bf16 v[12:15], v[136:139], v[206:209], v[12:15]
	v_mfma_f32_16x16x32_bf16 v[12:15], v[140:143], v[210:213], v[12:15]
	v_mfma_f32_16x16x32_bf16 v[4:7], v[160:163], v[206:209], v[4:7]
	v_mfma_f32_16x16x32_bf16 v[4:7], v[170:173], v[210:213], v[4:7]
	v_mfma_f32_16x16x32_bf16 v[0:3], v[174:177], v[206:209], v[0:3]
	v_mfma_f32_16x16x32_bf16 v[0:3], v[178:181], v[210:213], v[0:3]
	s_setprio 0
	s_barrier
	s_add_i32 s58, 0, 0x18000
	s_add_i32 s59, 0, 0x1c000
	v_add_u32_e32 v140, s58, v165
	v_add_u32_e32 v178, s59, v165
	ds_read_b128 v[128:131], v140
	ds_read_b128 v[132:135], v140 offset:1024
	ds_read_b128 v[136:139], v140 offset:2048
	ds_read_b128 v[140:143], v140 offset:3072
	ds_read_b128 v[160:163], v178
	ds_read_b128 v[170:173], v178 offset:1024
	ds_read_b128 v[174:177], v178 offset:2048
	ds_read_b128 v[178:181], v178 offset:3072
	s_add_u32 s14, s20, 0x2b0000
	s_addc_u32 s15, s21, 0
	s_mov_b32 m0, s27
	v_lshl_add_u64 v[222:223], s[14:15], 0, v[144:145]
	ds_read_b128 v[182:185], v169 offset:32768
	ds_read_b128 v[186:189], v169 offset:33792
	ds_read_b128 v[190:193], v169 offset:34816
	ds_read_b128 v[194:197], v169 offset:35840
	ds_read_b128 v[198:201], v169 offset:36864
	ds_read_b128 v[202:205], v169 offset:37888
	ds_read_b128 v[206:209], v169 offset:38912
	ds_read_b128 v[210:213], v169 offset:39936
	global_load_lds_dwordx4 v[222:223], off
	v_lshl_add_u64 v[222:223], s[14:15], 0, v[148:149]
	s_mov_b32 m0, s28
	s_nop 0
	global_load_lds_dwordx4 v[222:223], off
	s_waitcnt vmcnt(8)
	s_waitcnt lgkmcnt(0)
	s_barrier
	s_setprio 1
	s_waitcnt lgkmcnt(0)
	v_mfma_f32_16x16x32_bf16 v[124:127], v[128:131], v[182:185], v[124:127]
	v_mfma_f32_16x16x32_bf16 v[124:127], v[132:135], v[186:189], v[124:127]
	v_mfma_f32_16x16x32_bf16 v[120:123], v[136:139], v[182:185], v[120:123]
	v_mfma_f32_16x16x32_bf16 v[120:123], v[140:143], v[186:189], v[120:123]
	v_mfma_f32_16x16x32_bf16 v[112:115], v[160:163], v[182:185], v[112:115]
	v_mfma_f32_16x16x32_bf16 v[112:115], v[170:173], v[186:189], v[112:115]
	v_mfma_f32_16x16x32_bf16 v[104:107], v[174:177], v[182:185], v[104:107]
	v_mfma_f32_16x16x32_bf16 v[104:107], v[178:181], v[186:189], v[104:107]
	v_mfma_f32_16x16x32_bf16 v[116:119], v[128:131], v[190:193], v[116:119]
	v_mfma_f32_16x16x32_bf16 v[116:119], v[132:135], v[194:197], v[116:119]
	v_mfma_f32_16x16x32_bf16 v[108:111], v[136:139], v[190:193], v[108:111]
	v_mfma_f32_16x16x32_bf16 v[108:111], v[140:143], v[194:197], v[108:111]
	v_mfma_f32_16x16x32_bf16 v[100:103], v[160:163], v[190:193], v[100:103]
	v_mfma_f32_16x16x32_bf16 v[100:103], v[170:173], v[194:197], v[100:103]
	v_mfma_f32_16x16x32_bf16 v[96:99], v[174:177], v[190:193], v[96:99]
	v_mfma_f32_16x16x32_bf16 v[96:99], v[178:181], v[194:197], v[96:99]
	v_mfma_f32_16x16x32_bf16 v[92:95], v[128:131], v[198:201], v[92:95]
	v_mfma_f32_16x16x32_bf16 v[92:95], v[132:135], v[202:205], v[92:95]
	v_mfma_f32_16x16x32_bf16 v[88:91], v[136:139], v[198:201], v[88:91]
	v_mfma_f32_16x16x32_bf16 v[88:91], v[140:143], v[202:205], v[88:91]
	v_mfma_f32_16x16x32_bf16 v[84:87], v[160:163], v[198:201], v[84:87]
	v_mfma_f32_16x16x32_bf16 v[84:87], v[170:173], v[202:205], v[84:87]
	v_mfma_f32_16x16x32_bf16 v[76:79], v[174:177], v[198:201], v[76:79]
	v_mfma_f32_16x16x32_bf16 v[76:79], v[178:181], v[202:205], v[76:79]
	v_mfma_f32_16x16x32_bf16 v[80:83], v[128:131], v[206:209], v[80:83]
	v_mfma_f32_16x16x32_bf16 v[80:83], v[132:135], v[210:213], v[80:83]
	v_mfma_f32_16x16x32_bf16 v[72:75], v[136:139], v[206:209], v[72:75]
	v_mfma_f32_16x16x32_bf16 v[72:75], v[140:143], v[210:213], v[72:75]
	v_mfma_f32_16x16x32_bf16 v[68:71], v[160:163], v[206:209], v[68:71]
	v_mfma_f32_16x16x32_bf16 v[68:71], v[170:173], v[210:213], v[68:71]
	v_mfma_f32_16x16x32_bf16 v[64:67], v[174:177], v[206:209], v[64:67]
	v_mfma_f32_16x16x32_bf16 v[64:67], v[178:181], v[210:213], v[64:67]
	s_setprio 0
	s_barrier
; #define PG8_STAGE(bufoff, gbase, voff) do { _Pragma("unroll") for (int _i = 0; _i < 2; ++_i) \
;         __builtin_amdgcn_global_load_lds((const unsigned*)((const char*)(gbase) + (voff)[_i]), (PG8_LAS unsigned*)(lds + (bufoff) + ldsw + _i * 8192), 16, 0, 0); } while (0)
; #define PG8_LDA(dst, b, h) do { _Pragma("unroll") for (int m = 0; m < 4; ++m) _Pragma("unroll") for (int k = 0; k < 2; ++k) dst[m][k] = *(const PG8_LAS bf16x8*)(lds + PG8_SA(b, h) + aoff + m * 2048 + k * 1024); } while (0)
; #define PG8_MMA(ai, bj, At, Bt) do { __builtin_amdgcn_s_setprio(1); _Pragma("unroll") for (int m = 0; m < 4; ++m) _Pragma("unroll") for (int n = 0; n < 2; ++n) _Pragma("unroll") for (int k = 0; k < 2; ++k) \
;         acc[ai][bj][m][n] = __builtin_amdgcn_mfma_f32_16x16x32_bf16(Bt[n][k], At[m][k], acc[ai][bj][m][n], 0, 0, 0); __builtin_amdgcn_s_setprio(0); } while (0)
; #define PG8_WAIT_V(n) asm volatile("s_waitcnt vmcnt(" #n ")" ::: "memory")
; #define PG8_WAIT_L(n) asm volatile("s_waitcnt lgkmcnt(" #n ")" ::: "memory")
; #define PG8_BAR __builtin_amdgcn_s_barrier()
; #define PG8_SCHED __builtin_amdgcn_sched_barrier(0)
; template <class Epi, class Sched, bool ALIGN_EPI = false, bool SP2 = false>
; __device__ __forceinline__ void gemm_phase(PG8_LAS unsigned char* lds, const Gemm g, const Sched& S, const Epi& E) {
;     ...
;         for (int t = 0; t < nt; t += 2) {
;             const bool last = (t == nt - 2);
;             const char* a1 = cA + (size_t)(t + 1) * kstep;
;             const char* a2 = last ? nA : cA + (size_t)(t + 2) * kstep; const char* b2 = last ? nB : cB + (size_t)(t + 2) * kstep;
;     ...
;             PG8_LDA(At, 1, 1); PG8_STAGE(PG8_SB(1, 0), b3, voffB); PG8_STAGE(PG8_SB(1, 1), b3 + hstepB, voffB); PG8_STAGE(PG8_SA(1, 0), a3, voffA);
;             PG8_WAIT_V(8); PG8_WAIT_L(0); PG8_BAR; PG8_MMA(1, 0, At, B0); PG8_MMA(1, 1, At, B1); PG8_BAR; PG8_SCHED;
	s_add_i32 s14, s58, s24
	v_lshl_add_u64 v[214:215], v[214:215], 0, s[8:9]
	s_mov_b32 m0, s14
	ds_read_b128 v[182:185], v169 offset:49152
	ds_read_b128 v[186:189], v169 offset:50176
	ds_read_b128 v[190:193], v169 offset:51200
	ds_read_b128 v[194:197], v169 offset:52224
	ds_read_b128 v[198:201], v169 offset:53248
	ds_read_b128 v[202:205], v169 offset:54272
	ds_read_b128 v[206:209], v169 offset:55296
	ds_read_b128 v[210:213], v169 offset:56320
	global_load_lds_dwordx4 v[214:215], off
	s_add_i32 m0, s14, 0x2000
	s_add_u32 s14, s18, 0x2b0080
	v_lshl_add_u64 v[214:215], v[216:217], 0, s[8:9]
	s_addc_u32 s15, s19, 0
	s_add_i32 s18, s59, s24
	global_load_lds_dwordx4 v[214:215], off
	v_lshl_add_u64 v[214:215], s[14:15], 0, v[146:147]
	s_mov_b32 m0, s18
	s_nop 0
	global_load_lds_dwordx4 v[214:215], off
	v_lshl_add_u64 v[214:215], s[14:15], 0, v[150:151]
	s_add_i32 m0, s18, 0x2000
	s_nop 0
	global_load_lds_dwordx4 v[214:215], off
	v_lshl_add_u64 v[214:215], v[218:219], 0, s[8:9]
	s_mov_b32 m0, s33
	s_nop 0
	global_load_lds_dwordx4 v[214:215], off
	v_lshl_add_u64 v[214:215], v[220:221], 0, s[8:9]
	s_mov_b32 m0, s34
	s_nop 0
	global_load_lds_dwordx4 v[214:215], off
	s_waitcnt vmcnt(8)
	s_waitcnt lgkmcnt(0)
	s_barrier
	s_setprio 1
	s_waitcnt lgkmcnt(0)
	v_mfma_f32_16x16x32_bf16 v[60:63], v[128:131], v[182:185], v[60:63]
	v_mfma_f32_16x16x32_bf16 v[60:63], v[132:135], v[186:189], v[60:63]
	v_mfma_f32_16x16x32_bf16 v[56:59], v[136:139], v[182:185], v[56:59]
	v_mfma_f32_16x16x32_bf16 v[56:59], v[140:143], v[186:189], v[56:59]
	v_mfma_f32_16x16x32_bf16 v[52:55], v[160:163], v[182:185], v[52:55]
	v_mfma_f32_16x16x32_bf16 v[52:55], v[170:173], v[186:189], v[52:55]
	v_mfma_f32_16x16x32_bf16 v[44:47], v[174:177], v[182:185], v[44:47]
	v_mfma_f32_16x16x32_bf16 v[44:47], v[178:181], v[186:189], v[44:47]
	v_mfma_f32_16x16x32_bf16 v[48:51], v[128:131], v[190:193], v[48:51]
	v_mfma_f32_16x16x32_bf16 v[48:51], v[132:135], v[194:197], v[48:51]
	v_mfma_f32_16x16x32_bf16 v[40:43], v[136:139], v[190:193], v[40:43]
	v_mfma_f32_16x16x32_bf16 v[40:43], v[140:143], v[194:197], v[40:43]
	v_mfma_f32_16x16x32_bf16 v[36:39], v[160:163], v[190:193], v[36:39]
	v_mfma_f32_16x16x32_bf16 v[36:39], v[170:173], v[194:197], v[36:39]
	v_mfma_f32_16x16x32_bf16 v[32:35], v[174:177], v[190:193], v[32:35]
	v_mfma_f32_16x16x32_bf16 v[32:35], v[178:181], v[194:197], v[32:35]
	v_mfma_f32_16x16x32_bf16 v[28:31], v[128:131], v[198:201], v[28:31]
	v_mfma_f32_16x16x32_bf16 v[28:31], v[132:135], v[202:205], v[28:31]
	v_mfma_f32_16x16x32_bf16 v[24:27], v[136:139], v[198:201], v[24:27]
	v_mfma_f32_16x16x32_bf16 v[24:27], v[140:143], v[202:205], v[24:27]
	v_mfma_f32_16x16x32_bf16 v[16:19], v[160:163], v[198:201], v[16:19]
	v_mfma_f32_16x16x32_bf16 v[16:19], v[170:173], v[202:205], v[16:19]
	v_mfma_f32_16x16x32_bf16 v[8:11], v[174:177], v[198:201], v[8:11]
	v_mfma_f32_16x16x32_bf16 v[8:11], v[178:181], v[202:205], v[8:11]
	v_mfma_f32_16x16x32_bf16 v[20:23], v[128:131], v[206:209], v[20:23]
	v_mfma_f32_16x16x32_bf16 v[20:23], v[132:135], v[210:213], v[20:23]
	v_mfma_f32_16x16x32_bf16 v[12:15], v[136:139], v[206:209], v[12:15]
	v_mfma_f32_16x16x32_bf16 v[12:15], v[140:143], v[210:213], v[12:15]
	v_mfma_f32_16x16x32_bf16 v[4:7], v[160:163], v[206:209], v[4:7]
	v_mfma_f32_16x16x32_bf16 v[4:7], v[170:173], v[210:213], v[4:7]
	v_mfma_f32_16x16x32_bf16 v[0:3], v[174:177], v[206:209], v[0:3]
	v_mfma_f32_16x16x32_bf16 v[0:3], v[178:181], v[210:213], v[0:3]
	s_setprio 0
	s_barrier
	s_add_i32 s57, s57, 2
	s_add_u32 s55, s55, 0x100
	s_addc_u32 s56, s56, 0
	s_cmpk_gt_u32 s57, 0xa9
	s_mov_b64 s[14:15], s[16:17]
	s_cbranch_scc0 .LBB0_2165
	s_and_b64 vcc, exec, s[10:11]
	s_cbranch_vccz .LBB0_2168
	s_barrier
